# loop-edge edit: K-loop tail pointer increments issued in the shadow of the last MFMA run (on combined+final version)
# speedup vs baseline: 1.0015x; 1.0015x over previous
; #define PG8_STAGE(bufoff, gbase, voff) do { _Pragma("unroll") for (int _i = 0; _i < 2; ++_i) \
;         __builtin_amdgcn_global_load_lds((const unsigned*)((const char*)(gbase) + (voff)[_i]), (LAS unsigned*)(lds + (bufoff) + ldsw + _i * 8192), 16, 0, 0); } while (0)
; #define PG8_LDA(dst, b, h) do { _Pragma("unroll") for (int m = 0; m < 4; ++m) _Pragma("unroll") for (int k = 0; k < 2; ++k) dst[m][k] = *(const LAS bf16x8*)(lds + PG8_SA(b, h) + aoff + m * 2048 + k * 1024); } while (0)
; #define PG8_MMA(ai, bj, At, Bt) do { __builtin_amdgcn_s_setprio(1); _Pragma("unroll") for (int m = 0; m < 4; ++m) _Pragma("unroll") for (int n = 0; n < 2; ++n) _Pragma("unroll") for (int k = 0; k < 2; ++k) \
;         acc[ai][bj][m][n] = __builtin_amdgcn_mfma_f32_16x16x32_bf16(Bt[n][k], At[m][k], acc[ai][bj][m][n], 0, 0, 0); __builtin_amdgcn_s_setprio(0); } while (0)
; #define PG8_WAIT_V(n) asm volatile("s_waitcnt vmcnt(" #n ")" ::: "memory")
; #define PG8_WAIT_L(n) asm volatile("s_waitcnt lgkmcnt(" #n ")" ::: "memory")
; #define PG8_BAR __builtin_amdgcn_s_barrier()
; #define PG8_SCHED __builtin_amdgcn_sched_barrier(0)
; template <class Epi, bool ALIGN_EPI = true>
; __device__ __forceinline__ void gemm_phase(LAS unsigned char* lds, const Gemm g, const Sched& S, const Epi& E) {
;     ...
;         for (int t = t_lo; t < t_hi; t += 2) {
;     ...
;             PG8_WAIT_V(8); PG8_WAIT_L(0); PG8_BAR; PG8_MMA(0, 0, At, B0); PG8_MMA(0, 1, At, B1); PG8_BAR; PG8_SCHED;
;             PG8_LDA(At, 1, 1); PG8_STAGE(PG8_SB(1, 0), b3, voffB); PG8_STAGE(PG8_SB(1, 1), b3 + hstepB, voffB); PG8_STAGE(PG8_SA(1, 0), a3, voffA);
;             PG8_WAIT_V(8); PG8_WAIT_L(0); PG8_BAR; PG8_MMA(1, 0, At, B0); PG8_MMA(1, 1, At, B1); PG8_BAR; PG8_SCHED;
;         }
.Lx4last_3:
	s_waitcnt vmcnt(6) lgkmcnt(0)
	s_barrier
	s_setprio 1
	v_mfma_f32_16x16x32_bf16 v[66:69], v[134:137], v[178:181], v[66:69]
	v_mfma_f32_16x16x32_bf16 v[62:65], v[142:145], v[178:181], v[62:65]
	v_mfma_f32_16x16x32_bf16 v[58:61], v[134:137], v[192:195], v[58:61]
	v_mfma_f32_16x16x32_bf16 v[54:57], v[142:145], v[192:195], v[54:57]
	v_mfma_f32_16x16x32_bf16 v[50:53], v[134:137], v[224:227], v[50:53]
	v_mfma_f32_16x16x32_bf16 v[46:49], v[142:145], v[224:227], v[46:49]
	v_mfma_f32_16x16x32_bf16 v[42:45], v[134:137], v[232:235], v[42:45]
	v_mfma_f32_16x16x32_bf16 v[38:41], v[142:145], v[232:235], v[38:41]
	v_mfma_f32_16x16x32_bf16 v[66:69], v[138:141], v[188:191], v[66:69]
	v_mfma_f32_16x16x32_bf16 v[62:65], v[146:149], v[188:191], v[62:65]
	v_mfma_f32_16x16x32_bf16 v[58:61], v[138:141], v[206:209], v[58:61]
	v_mfma_f32_16x16x32_bf16 v[54:57], v[146:149], v[206:209], v[54:57]
	v_mfma_f32_16x16x32_bf16 v[50:53], v[138:141], v[228:231], v[50:53]
	v_mfma_f32_16x16x32_bf16 v[46:49], v[146:149], v[228:231], v[46:49]
	v_mfma_f32_16x16x32_bf16 v[42:45], v[138:141], v[236:239], v[42:45]
	v_mfma_f32_16x16x32_bf16 v[38:41], v[146:149], v[236:239], v[38:41]
	s_setprio 0
	s_setprio 1
	s_add_u32 s4, s4, 0x100
	s_addc_u32 s5, s5, 0
	s_add_u32 s20, s20, 0x100
	s_addc_u32 s21, s21, 0
	v_mfma_f32_16x16x32_bf16 v[34:37], v[162:165], v[178:181], v[34:37]
	v_mfma_f32_16x16x32_bf16 v[30:33], v[170:173], v[178:181], v[30:33]
	v_mfma_f32_16x16x32_bf16 v[26:29], v[162:165], v[192:195], v[26:29]
	v_mfma_f32_16x16x32_bf16 v[22:25], v[170:173], v[192:195], v[22:25]
	v_mfma_f32_16x16x32_bf16 v[18:21], v[162:165], v[224:227], v[18:21]
	v_mfma_f32_16x16x32_bf16 v[14:17], v[170:173], v[224:227], v[14:17]
	v_mfma_f32_16x16x32_bf16 v[8:11], v[162:165], v[232:235], v[10:13]
	v_mfma_f32_16x16x32_bf16 v[4:7], v[170:173], v[232:235], v[4:7]
	v_mfma_f32_16x16x32_bf16 v[34:37], v[166:169], v[188:191], v[34:37]
	v_mfma_f32_16x16x32_bf16 v[30:33], v[174:177], v[188:191], v[30:33]
	v_mfma_f32_16x16x32_bf16 v[26:29], v[166:169], v[206:209], v[26:29]
	v_mfma_f32_16x16x32_bf16 v[22:25], v[174:177], v[206:209], v[22:25]
	v_mfma_f32_16x16x32_bf16 v[18:21], v[166:169], v[228:231], v[18:21]
	v_mfma_f32_16x16x32_bf16 v[14:17], v[174:177], v[228:231], v[14:17]
	v_mfma_f32_16x16x32_bf16 v[10:13], v[166:169], v[236:239], v[8:11]
	v_mfma_f32_16x16x32_bf16 v[6:9], v[174:177], v[236:239], v[4:7]
	s_setprio 0
	s_barrier
	s_cmp_ge_i32 s22, s46
	s_mov_b32 s6, s22
	s_cbranch_scc0 .LBB0_500
	s_add_i32 s14, s27, 0x1c000
	s_mov_b32 s23, 0x18000
	s_mov_b32 s24, 0x1c000
	s_mov_b32 s52, 0x14000

; #define PG8_STAGE(bufoff, gbase, voff) do { _Pragma("unroll") for (int _i = 0; _i < 2; ++_i) \
;         __builtin_amdgcn_global_load_lds((const unsigned*)((const char*)(gbase) + (voff)[_i]), (LAS unsigned*)(lds + (bufoff) + ldsw + _i * 8192), 16, 0, 0); } while (0)
; #define PG8_LDA(dst, b, h) do { _Pragma("unroll") for (int m = 0; m < 4; ++m) _Pragma("unroll") for (int k = 0; k < 2; ++k) dst[m][k] = *(const LAS bf16x8*)(lds + PG8_SA(b, h) + aoff + m * 2048 + k * 1024); } while (0)
; #define PG8_MMA(ai, bj, At, Bt) do { __builtin_amdgcn_s_setprio(1); _Pragma("unroll") for (int m = 0; m < 4; ++m) _Pragma("unroll") for (int n = 0; n < 2; ++n) _Pragma("unroll") for (int k = 0; k < 2; ++k) \
;         acc[ai][bj][m][n] = __builtin_amdgcn_mfma_f32_16x16x32_bf16(Bt[n][k], At[m][k], acc[ai][bj][m][n], 0, 0, 0); __builtin_amdgcn_s_setprio(0); } while (0)
; #define PG8_WAIT_V(n) asm volatile("s_waitcnt vmcnt(" #n ")" ::: "memory")
; #define PG8_WAIT_L(n) asm volatile("s_waitcnt lgkmcnt(" #n ")" ::: "memory")
; #define PG8_BAR __builtin_amdgcn_s_barrier()
; #define PG8_SCHED __builtin_amdgcn_sched_barrier(0)
; template <class Epi, bool ALIGN_EPI = true>
; __device__ __forceinline__ void gemm_phase(LAS unsigned char* lds, const Gemm g, const Sched& S, const Epi& E) {
;     ...
;         for (int t = t_lo; t < t_hi; t += 2) {
;     ...
;             PG8_WAIT_V(8); PG8_WAIT_L(0); PG8_BAR; PG8_MMA(0, 0, At, B0); PG8_MMA(0, 1, At, B1); PG8_BAR; PG8_SCHED;
;             PG8_LDA(At, 1, 1); PG8_STAGE(PG8_SB(1, 0), b3, voffB); PG8_STAGE(PG8_SB(1, 1), b3 + hstepB, voffB); PG8_STAGE(PG8_SA(1, 0), a3, voffA);
;             PG8_WAIT_V(8); PG8_WAIT_L(0); PG8_BAR; PG8_MMA(1, 0, At, B0); PG8_MMA(1, 1, At, B1); PG8_BAR; PG8_SCHED;
;         }
.Lx4last_6:
	s_waitcnt vmcnt(6) lgkmcnt(0)
	s_barrier
	s_setprio 1
	v_mfma_f32_16x16x32_bf16 v[66:69], v[134:137], v[178:181], v[66:69]
	v_mfma_f32_16x16x32_bf16 v[62:65], v[142:145], v[178:181], v[62:65]
	v_mfma_f32_16x16x32_bf16 v[58:61], v[134:137], v[192:195], v[58:61]
	v_mfma_f32_16x16x32_bf16 v[54:57], v[142:145], v[192:195], v[54:57]
	v_mfma_f32_16x16x32_bf16 v[50:53], v[134:137], v[224:227], v[50:53]
	v_mfma_f32_16x16x32_bf16 v[46:49], v[142:145], v[224:227], v[46:49]
	v_mfma_f32_16x16x32_bf16 v[42:45], v[134:137], v[232:235], v[42:45]
	v_mfma_f32_16x16x32_bf16 v[38:41], v[142:145], v[232:235], v[38:41]
	v_mfma_f32_16x16x32_bf16 v[66:69], v[138:141], v[188:191], v[66:69]
	v_mfma_f32_16x16x32_bf16 v[62:65], v[146:149], v[188:191], v[62:65]
	v_mfma_f32_16x16x32_bf16 v[58:61], v[138:141], v[206:209], v[58:61]
	v_mfma_f32_16x16x32_bf16 v[54:57], v[146:149], v[206:209], v[54:57]
	v_mfma_f32_16x16x32_bf16 v[50:53], v[138:141], v[228:231], v[50:53]
	v_mfma_f32_16x16x32_bf16 v[46:49], v[146:149], v[228:231], v[46:49]
	v_mfma_f32_16x16x32_bf16 v[42:45], v[138:141], v[236:239], v[42:45]
	v_mfma_f32_16x16x32_bf16 v[38:41], v[146:149], v[236:239], v[38:41]
	s_setprio 0
	s_setprio 1
	s_add_u32 s4, s4, 0x100
	s_addc_u32 s5, s5, 0
	s_add_u32 s20, s20, 0x100
	s_addc_u32 s21, s21, 0
	v_mfma_f32_16x16x32_bf16 v[34:37], v[162:165], v[178:181], v[34:37]
	v_mfma_f32_16x16x32_bf16 v[30:33], v[170:173], v[178:181], v[30:33]
	v_mfma_f32_16x16x32_bf16 v[26:29], v[162:165], v[192:195], v[26:29]
	v_mfma_f32_16x16x32_bf16 v[22:25], v[170:173], v[192:195], v[22:25]
	v_mfma_f32_16x16x32_bf16 v[18:21], v[162:165], v[224:227], v[18:21]
	v_mfma_f32_16x16x32_bf16 v[14:17], v[170:173], v[224:227], v[14:17]
	v_mfma_f32_16x16x32_bf16 v[8:11], v[162:165], v[232:235], v[10:13]
	v_mfma_f32_16x16x32_bf16 v[4:7], v[170:173], v[232:235], v[4:7]
	v_mfma_f32_16x16x32_bf16 v[34:37], v[166:169], v[188:191], v[34:37]
	v_mfma_f32_16x16x32_bf16 v[30:33], v[174:177], v[188:191], v[30:33]
	v_mfma_f32_16x16x32_bf16 v[26:29], v[166:169], v[206:209], v[26:29]
	v_mfma_f32_16x16x32_bf16 v[22:25], v[174:177], v[206:209], v[22:25]
	v_mfma_f32_16x16x32_bf16 v[18:21], v[166:169], v[228:231], v[18:21]
	v_mfma_f32_16x16x32_bf16 v[14:17], v[174:177], v[228:231], v[14:17]
	v_mfma_f32_16x16x32_bf16 v[10:13], v[166:169], v[236:239], v[8:11]
	v_mfma_f32_16x16x32_bf16 v[6:9], v[174:177], v[236:239], v[4:7]
	s_setprio 0
	s_barrier
	s_cmp_ge_i32 s22, s31
	s_mov_b32 s6, s22
	s_cbranch_scc0 .LBB0_954
	s_add_i32 s14, s94, 0x1c000
	s_mov_b32 s23, 0x18000
	s_mov_b32 s24, 0x1c000
	s_mov_b32 s58, 0x14000

; #define PG8_STAGE(bufoff, gbase, voff) do { _Pragma("unroll") for (int _i = 0; _i < 2; ++_i) \
;         __builtin_amdgcn_global_load_lds((const unsigned*)((const char*)(gbase) + (voff)[_i]), (LAS unsigned*)(lds + (bufoff) + ldsw + _i * 8192), 16, 0, 0); } while (0)
; #define PG8_LDA(dst, b, h) do { _Pragma("unroll") for (int m = 0; m < 4; ++m) _Pragma("unroll") for (int k = 0; k < 2; ++k) dst[m][k] = *(const LAS bf16x8*)(lds + PG8_SA(b, h) + aoff + m * 2048 + k * 1024); } while (0)
; #define PG8_LDB(dst, b, h) do { _Pragma("unroll") for (int n = 0; n < 2; ++n) _Pragma("unroll") for (int k = 0; k < 2; ++k) dst[n][k] = *(const LAS bf16x8*)(lds + PG8_SB(b, h) + boff + n * 2048 + k * 1024); } while (0)
; #define PG8_MMA(ai, bj, At, Bt) do { __builtin_amdgcn_s_setprio(1); _Pragma("unroll") for (int m = 0; m < 4; ++m) _Pragma("unroll") for (int n = 0; n < 2; ++n) _Pragma("unroll") for (int k = 0; k < 2; ++k) \
;         acc[ai][bj][m][n] = __builtin_amdgcn_mfma_f32_16x16x32_bf16(Bt[n][k], At[m][k], acc[ai][bj][m][n], 0, 0, 0); __builtin_amdgcn_s_setprio(0); } while (0)
; template <class Epi, bool ALIGN_EPI = true>
; __device__ __forceinline__ void gemm_phase(LAS unsigned char* lds, const Gemm g, const Sched& S, const Epi& E) {
;     ...
;         for (int t = t_lo; t < t_hi; t += 2) {
;             const bool last = (t == nt - 2);
;             const char* a1 = cA + (size_t)(t + 1) * kstep;
;             const char* a2 = last ? nA : cA + (size_t)(t + 2) * kstep; const char* b2 = last ? nB : cB + (size_t)(t + 2) * kstep;
;             const char* a3 = a2 + kstep; const char* b3 = b2 + kstep;
;             const int rflag = __builtin_amdgcn_readfirstlane(t | (int)(ui == 0));
;             PG8_LDB(B0, 0, 0); PG8_LDB(B1, 0, 1); PG8_SCHED; PG8_LDA(At, 0, 0); PG8_STAGE(PG8_SA(1, 1), a1 + hstepA, voffA);
;             if constexpr (Epi::NSTORES > 0) PG8_WAIT_RELAX(rflag, 8 + Epi::NSTORES); else PG8_WAIT_V(8);
;             PG8_WAIT_L(0); PG8_BAR; PG8_MMA(0, 0, At, B0); PG8_MMA(0, 1, At, B1); PG8_BAR; PG8_SCHED;
;             PG8_LDA(At, 0, 1); PG8_STAGE(PG8_SB(0, 0), b2, voffB); PG8_STAGE(PG8_SB(0, 1), b2 + hstepB, voffB); PG8_STAGE(PG8_SA(0, 0), a2, voffA);
;             if constexpr (Epi::NSTORES > 0) PG8_WAIT_RELAX(rflag, 8 + Epi::NSTORES); else PG8_WAIT_V(8);
;             PG8_WAIT_L(0); PG8_BAR; PG8_MMA(1, 0, At, B0); PG8_MMA(1, 1, At, B1); PG8_BAR; PG8_SCHED;
.LBB0_1311:
	s_add_i32 s67, s48, 2
	s_add_u32 s49, s46, 0xfff80080
	s_addc_u32 s50, s47, -1
	s_cmp_eq_u32 s59, s48
	s_cselect_b32 s51, s21, s50
	s_cselect_b32 s50, s23, s49
	s_cselect_b32 s49, s63, s66
	s_cselect_b32 s48, s64, s65
	s_add_u32 s100, s46, 0xfff80000
	s_addc_u32 s101, s47, -1
	ds_read_b128 v[150:153], v147
	ds_read_b128 v[154:157], v147 offset:1024
	ds_read_b128 v[158:161], v147 offset:2048
	ds_read_b128 v[162:165], v147 offset:3072
	ds_read_b128 v[166:169], v147 offset:16384
	ds_read_b128 v[170:173], v147 offset:17408
	ds_read_b128 v[174:177], v147 offset:18432
	ds_read_b128 v[178:181], v147 offset:19456
	ds_read_b128 v[182:185], v148
	ds_read_b128 v[186:189], v148 offset:1024
	ds_read_b128 v[190:193], v148 offset:2048
	ds_read_b128 v[194:197], v148 offset:3072
	s_mov_b32 m0, s57
	ds_read_b128 v[206:209], v148 offset:4096
	global_load_lds_dwordx4 v142, s[100:101]
	s_mov_b32 m0, s58
	ds_read_b128 v[224:227], v148 offset:5120
	global_load_lds_dwordx4 v144, s[100:101]
	s_add_i32 m0, s52, 0xc000
	ds_read_b128 v[228:231], v148 offset:6144
	global_load_lds_dwordx4 v142, s[46:47]
	s_add_i32 m0, s52, 0xe000
	ds_read_b128 v[232:235], v148 offset:7168
	global_load_lds_dwordx4 v144, s[46:47]
	s_waitcnt vmcnt(8) lgkmcnt(0)
	s_barrier
	s_setprio 1
	v_mfma_f32_16x16x32_bf16 v[130:133], v[150:153], v[182:185], v[130:133]
	v_mfma_f32_16x16x32_bf16 v[126:129], v[158:161], v[182:185], v[126:129]
	v_mfma_f32_16x16x32_bf16 v[114:117], v[150:153], v[190:193], v[114:117]
	v_mfma_f32_16x16x32_bf16 v[110:113], v[158:161], v[190:193], v[110:113]
	v_mfma_f32_16x16x32_bf16 v[98:101], v[150:153], v[206:209], v[98:101]
	v_mfma_f32_16x16x32_bf16 v[94:97], v[158:161], v[206:209], v[94:97]
	v_mfma_f32_16x16x32_bf16 v[82:85], v[150:153], v[228:231], v[82:85]
	v_mfma_f32_16x16x32_bf16 v[78:81], v[158:161], v[228:231], v[78:81]
	v_mfma_f32_16x16x32_bf16 v[130:133], v[154:157], v[186:189], v[130:133]
	v_mfma_f32_16x16x32_bf16 v[126:129], v[162:165], v[186:189], v[126:129]
	v_mfma_f32_16x16x32_bf16 v[114:117], v[154:157], v[194:197], v[114:117]
	v_mfma_f32_16x16x32_bf16 v[110:113], v[162:165], v[194:197], v[110:113]
	v_mfma_f32_16x16x32_bf16 v[98:101], v[154:157], v[224:227], v[98:101]
	v_mfma_f32_16x16x32_bf16 v[94:97], v[162:165], v[224:227], v[94:97]
	v_mfma_f32_16x16x32_bf16 v[82:85], v[154:157], v[232:235], v[82:85]
	v_mfma_f32_16x16x32_bf16 v[78:81], v[162:165], v[232:235], v[78:81]
	s_setprio 0
	s_setprio 1
	v_mfma_f32_16x16x32_bf16 v[122:125], v[166:169], v[182:185], v[122:125]
	v_mfma_f32_16x16x32_bf16 v[118:121], v[174:177], v[182:185], v[118:121]
	v_mfma_f32_16x16x32_bf16 v[106:109], v[166:169], v[190:193], v[106:109]
	v_mfma_f32_16x16x32_bf16 v[102:105], v[174:177], v[190:193], v[102:105]
	v_mfma_f32_16x16x32_bf16 v[90:93], v[166:169], v[206:209], v[90:93]
	v_mfma_f32_16x16x32_bf16 v[86:89], v[174:177], v[206:209], v[86:89]
	v_mfma_f32_16x16x32_bf16 v[74:77], v[166:169], v[228:231], v[74:77]
	v_mfma_f32_16x16x32_bf16 v[70:73], v[174:177], v[228:231], v[70:73]
	v_mfma_f32_16x16x32_bf16 v[122:125], v[170:173], v[186:189], v[122:125]
	v_mfma_f32_16x16x32_bf16 v[118:121], v[178:181], v[186:189], v[118:121]
	v_mfma_f32_16x16x32_bf16 v[106:109], v[170:173], v[194:197], v[106:109]
	v_mfma_f32_16x16x32_bf16 v[102:105], v[178:181], v[194:197], v[102:105]
	v_mfma_f32_16x16x32_bf16 v[90:93], v[170:173], v[224:227], v[90:93]
	v_mfma_f32_16x16x32_bf16 v[86:89], v[178:181], v[224:227], v[86:89]
	v_mfma_f32_16x16x32_bf16 v[74:77], v[170:173], v[232:235], v[74:77]
	v_mfma_f32_16x16x32_bf16 v[70:73], v[178:181], v[232:235], v[70:73]
	s_setprio 0
	s_barrier
	s_add_u32 s68, s48, 0x80000
	s_addc_u32 s69, s49, 0
	ds_read_b128 v[182:185], v148 offset:16384
	ds_read_b128 v[186:189], v148 offset:17408
	ds_read_b128 v[190:193], v148 offset:18432
	ds_read_b128 v[194:197], v148 offset:19456
	s_add_i32 m0, s37, 0x10000
	ds_read_b128 v[206:209], v148 offset:20480
	global_load_lds_dwordx4 v138, s[48:49]
	s_add_i32 m0, s37, 0x12000
	ds_read_b128 v[224:227], v148 offset:21504
	global_load_lds_dwordx4 v134, s[48:49]
	s_add_i32 m0, s37, 0x14000
	ds_read_b128 v[228:231], v148 offset:22528
	global_load_lds_dwordx4 v138, s[68:69]
	s_add_i32 m0, s37, 0x16000
	ds_read_b128 v[232:235], v148 offset:23552
	global_load_lds_dwordx4 v134, s[68:69]
	s_waitcnt vmcnt(6) lgkmcnt(0)
	s_barrier
	s_setprio 1
	v_mfma_f32_16x16x32_bf16 v[66:69], v[150:153], v[182:185], v[66:69]
	v_mfma_f32_16x16x32_bf16 v[62:65], v[158:161], v[182:185], v[62:65]
	v_mfma_f32_16x16x32_bf16 v[50:53], v[150:153], v[190:193], v[50:53]
	v_mfma_f32_16x16x32_bf16 v[46:49], v[158:161], v[190:193], v[46:49]
	v_mfma_f32_16x16x32_bf16 v[34:37], v[150:153], v[206:209], v[34:37]
	v_mfma_f32_16x16x32_bf16 v[30:33], v[158:161], v[206:209], v[30:33]
	v_mfma_f32_16x16x32_bf16 v[18:21], v[150:153], v[228:231], v[18:21]
	v_mfma_f32_16x16x32_bf16 v[14:17], v[158:161], v[228:231], v[14:17]
	v_mfma_f32_16x16x32_bf16 v[66:69], v[154:157], v[186:189], v[66:69]
	v_mfma_f32_16x16x32_bf16 v[62:65], v[162:165], v[186:189], v[62:65]
	v_mfma_f32_16x16x32_bf16 v[50:53], v[154:157], v[194:197], v[50:53]
	v_mfma_f32_16x16x32_bf16 v[46:49], v[162:165], v[194:197], v[46:49]
	v_mfma_f32_16x16x32_bf16 v[34:37], v[154:157], v[224:227], v[34:37]
	v_mfma_f32_16x16x32_bf16 v[30:33], v[162:165], v[224:227], v[30:33]
	v_mfma_f32_16x16x32_bf16 v[18:21], v[154:157], v[232:235], v[18:21]
	v_mfma_f32_16x16x32_bf16 v[14:17], v[162:165], v[232:235], v[14:17]
	s_setprio 0
	s_setprio 1
	v_mfma_f32_16x16x32_bf16 v[58:61], v[166:169], v[182:185], v[58:61]
	v_mfma_f32_16x16x32_bf16 v[54:57], v[174:177], v[182:185], v[54:57]
	v_mfma_f32_16x16x32_bf16 v[42:45], v[166:169], v[190:193], v[42:45]
	v_mfma_f32_16x16x32_bf16 v[38:41], v[174:177], v[190:193], v[38:41]
	v_mfma_f32_16x16x32_bf16 v[26:29], v[166:169], v[206:209], v[26:29]
	v_mfma_f32_16x16x32_bf16 v[22:25], v[174:177], v[206:209], v[22:25]
	v_mfma_f32_16x16x32_bf16 v[10:13], v[166:169], v[228:231], v[10:13]
	v_mfma_f32_16x16x32_bf16 v[4:7], v[174:177], v[228:231], v[6:9]
	v_mfma_f32_16x16x32_bf16 v[58:61], v[170:173], v[186:189], v[58:61]
	v_mfma_f32_16x16x32_bf16 v[54:57], v[178:181], v[186:189], v[54:57]
	v_mfma_f32_16x16x32_bf16 v[42:45], v[170:173], v[194:197], v[42:45]
	v_mfma_f32_16x16x32_bf16 v[38:41], v[178:181], v[194:197], v[38:41]
	v_mfma_f32_16x16x32_bf16 v[26:29], v[170:173], v[224:227], v[26:29]
	v_mfma_f32_16x16x32_bf16 v[22:25], v[178:181], v[224:227], v[22:25]
	v_mfma_f32_16x16x32_bf16 v[10:13], v[170:173], v[232:235], v[10:13]
	v_mfma_f32_16x16x32_bf16 v[4:7], v[178:181], v[232:235], v[4:7]
	s_setprio 0
	s_barrier
; #define PG8_STAGE(bufoff, gbase, voff) do { _Pragma("unroll") for (int _i = 0; _i < 2; ++_i) \
;         __builtin_amdgcn_global_load_lds((const unsigned*)((const char*)(gbase) + (voff)[_i]), (LAS unsigned*)(lds + (bufoff) + ldsw + _i * 8192), 16, 0, 0); } while (0)
; #define PG8_LDA(dst, b, h) do { _Pragma("unroll") for (int m = 0; m < 4; ++m) _Pragma("unroll") for (int k = 0; k < 2; ++k) dst[m][k] = *(const LAS bf16x8*)(lds + PG8_SA(b, h) + aoff + m * 2048 + k * 1024); } while (0)
; #define PG8_LDB(dst, b, h) do { _Pragma("unroll") for (int n = 0; n < 2; ++n) _Pragma("unroll") for (int k = 0; k < 2; ++k) dst[n][k] = *(const LAS bf16x8*)(lds + PG8_SB(b, h) + boff + n * 2048 + k * 1024); } while (0)
; #define PG8_MMA(ai, bj, At, Bt) do { __builtin_amdgcn_s_setprio(1); _Pragma("unroll") for (int m = 0; m < 4; ++m) _Pragma("unroll") for (int n = 0; n < 2; ++n) _Pragma("unroll") for (int k = 0; k < 2; ++k) \
;         acc[ai][bj][m][n] = __builtin_amdgcn_mfma_f32_16x16x32_bf16(Bt[n][k], At[m][k], acc[ai][bj][m][n], 0, 0, 0); __builtin_amdgcn_s_setprio(0); } while (0)
; #define PG8_WAIT_V(n) asm volatile("s_waitcnt vmcnt(" #n ")" ::: "memory")
; #define PG8_WAIT_L(n) asm volatile("s_waitcnt lgkmcnt(" #n ")" ::: "memory")
; #define PG8_BAR __builtin_amdgcn_s_barrier()
; #define PG8_SCHED __builtin_amdgcn_sched_barrier(0)
; template <class Epi, bool ALIGN_EPI = true>
; __device__ __forceinline__ void gemm_phase(LAS unsigned char* lds, const Gemm g, const Sched& S, const Epi& E) {
;     ...
;         for (int t = t_lo; t < t_hi; t += 2) {
;     ...
;             PG8_LDB(B0, 1, 0); PG8_LDB(B1, 1, 1); PG8_SCHED; PG8_LDA(At, 1, 0); PG8_STAGE(PG8_SA(0, 1), a2 + hstepA, voffA);
;             PG8_WAIT_V(8); PG8_WAIT_L(0); PG8_BAR; PG8_MMA(0, 0, At, B0); PG8_MMA(0, 1, At, B1); PG8_BAR; PG8_SCHED;
;             PG8_LDA(At, 1, 1); PG8_STAGE(PG8_SB(1, 0), b3, voffB); PG8_STAGE(PG8_SB(1, 1), b3 + hstepB, voffB); PG8_STAGE(PG8_SA(1, 0), a3, voffA);
;             PG8_WAIT_V(8); PG8_WAIT_L(0); PG8_BAR; PG8_MMA(1, 0, At, B0); PG8_MMA(1, 1, At, B1); PG8_BAR; PG8_SCHED;
;         }
	s_mov_b64 s[100:101], s[50:51]
	s_add_u32 s50, s50, 0x80000
	s_addc_u32 s51, s51, 0
	ds_read_b128 v[150:153], v147 offset:32768
	ds_read_b128 v[154:157], v147 offset:33792
	ds_read_b128 v[158:161], v147 offset:34816
	ds_read_b128 v[162:165], v147 offset:35840
	ds_read_b128 v[166:169], v147 offset:49152
	ds_read_b128 v[170:173], v147 offset:50176
	ds_read_b128 v[174:177], v147 offset:51200
	ds_read_b128 v[178:181], v147 offset:52224
	ds_read_b128 v[182:185], v148 offset:32768
	ds_read_b128 v[186:189], v148 offset:33792
	ds_read_b128 v[190:193], v148 offset:34816
	ds_read_b128 v[194:197], v148 offset:35840
	s_mov_b32 m0, s52
	ds_read_b128 v[206:209], v148 offset:36864
	global_load_lds_dwordx4 v140, s[100:101]
	s_mov_b32 m0, s53
	ds_read_b128 v[224:227], v148 offset:37888
	global_load_lds_dwordx4 v136, s[100:101]
	s_mov_b32 m0, s54
	ds_read_b128 v[228:231], v148 offset:38912
	global_load_lds_dwordx4 v140, s[50:51]
	s_mov_b32 m0, s55
	ds_read_b128 v[232:235], v148 offset:39936
	global_load_lds_dwordx4 v136, s[50:51]
	s_waitcnt vmcnt(8) lgkmcnt(0)
	s_barrier
	s_setprio 1
	v_mfma_f32_16x16x32_bf16 v[130:133], v[150:153], v[182:185], v[130:133]
	v_mfma_f32_16x16x32_bf16 v[126:129], v[158:161], v[182:185], v[126:129]
	v_mfma_f32_16x16x32_bf16 v[114:117], v[150:153], v[190:193], v[114:117]
	v_mfma_f32_16x16x32_bf16 v[110:113], v[158:161], v[190:193], v[110:113]
	v_mfma_f32_16x16x32_bf16 v[98:101], v[150:153], v[206:209], v[98:101]
	v_mfma_f32_16x16x32_bf16 v[94:97], v[158:161], v[206:209], v[94:97]
	v_mfma_f32_16x16x32_bf16 v[82:85], v[150:153], v[228:231], v[82:85]
	v_mfma_f32_16x16x32_bf16 v[78:81], v[158:161], v[228:231], v[78:81]
	v_mfma_f32_16x16x32_bf16 v[130:133], v[154:157], v[186:189], v[130:133]
	v_mfma_f32_16x16x32_bf16 v[126:129], v[162:165], v[186:189], v[126:129]
	v_mfma_f32_16x16x32_bf16 v[114:117], v[154:157], v[194:197], v[114:117]
	v_mfma_f32_16x16x32_bf16 v[110:113], v[162:165], v[194:197], v[110:113]
	v_mfma_f32_16x16x32_bf16 v[98:101], v[154:157], v[224:227], v[98:101]
	v_mfma_f32_16x16x32_bf16 v[94:97], v[162:165], v[224:227], v[94:97]
	v_mfma_f32_16x16x32_bf16 v[82:85], v[154:157], v[232:235], v[82:85]
	v_mfma_f32_16x16x32_bf16 v[78:81], v[162:165], v[232:235], v[78:81]
	s_setprio 0
	s_setprio 1
	v_mfma_f32_16x16x32_bf16 v[122:125], v[166:169], v[182:185], v[122:125]
	v_mfma_f32_16x16x32_bf16 v[118:121], v[174:177], v[182:185], v[118:121]
	v_mfma_f32_16x16x32_bf16 v[106:109], v[166:169], v[190:193], v[106:109]
	v_mfma_f32_16x16x32_bf16 v[102:105], v[174:177], v[190:193], v[102:105]
	v_mfma_f32_16x16x32_bf16 v[90:93], v[166:169], v[206:209], v[90:93]
	v_mfma_f32_16x16x32_bf16 v[86:89], v[174:177], v[206:209], v[86:89]
	v_mfma_f32_16x16x32_bf16 v[74:77], v[166:169], v[228:231], v[74:77]
	v_mfma_f32_16x16x32_bf16 v[70:73], v[174:177], v[228:231], v[70:73]
	v_mfma_f32_16x16x32_bf16 v[122:125], v[170:173], v[186:189], v[122:125]
	v_mfma_f32_16x16x32_bf16 v[118:121], v[178:181], v[186:189], v[118:121]
	v_mfma_f32_16x16x32_bf16 v[106:109], v[170:173], v[194:197], v[106:109]
	v_mfma_f32_16x16x32_bf16 v[102:105], v[178:181], v[194:197], v[102:105]
	v_mfma_f32_16x16x32_bf16 v[90:93], v[170:173], v[224:227], v[90:93]
	v_mfma_f32_16x16x32_bf16 v[86:89], v[178:181], v[224:227], v[86:89]
	v_mfma_f32_16x16x32_bf16 v[74:77], v[170:173], v[232:235], v[74:77]
	v_mfma_f32_16x16x32_bf16 v[70:73], v[178:181], v[232:235], v[70:73]
	s_setprio 0
	s_barrier
	ds_read_b128 v[182:185], v148 offset:49152
	ds_read_b128 v[186:189], v148 offset:50176
	ds_read_b128 v[190:193], v148 offset:51200
	ds_read_b128 v[194:197], v148 offset:52224
	s_add_i32 m0, s37, 0x17f80
	ds_read_b128 v[206:209], v148 offset:53248
	global_load_lds_dwordx4 v138, s[48:49] offset:128
	s_add_i32 m0, s37, 0x19f80
	ds_read_b128 v[224:227], v148 offset:54272
	global_load_lds_dwordx4 v134, s[48:49] offset:128
	s_add_i32 m0, s37, 0x1c000
	s_add_u32 s48, s48, 0x80080
	s_addc_u32 s49, s49, 0
	ds_read_b128 v[228:231], v148 offset:55296
	global_load_lds_dwordx4 v138, s[48:49]
	s_add_i32 m0, s37, 0x1e000
	ds_read_b128 v[232:235], v148 offset:56320
	global_load_lds_dwordx4 v134, s[48:49]
	s_waitcnt vmcnt(6) lgkmcnt(0)
	s_barrier
	s_setprio 1
	v_mfma_f32_16x16x32_bf16 v[66:69], v[150:153], v[182:185], v[66:69]
	v_mfma_f32_16x16x32_bf16 v[62:65], v[158:161], v[182:185], v[62:65]
	v_mfma_f32_16x16x32_bf16 v[50:53], v[150:153], v[190:193], v[50:53]
	v_mfma_f32_16x16x32_bf16 v[46:49], v[158:161], v[190:193], v[46:49]
	v_mfma_f32_16x16x32_bf16 v[34:37], v[150:153], v[206:209], v[34:37]
	v_mfma_f32_16x16x32_bf16 v[30:33], v[158:161], v[206:209], v[30:33]
	v_mfma_f32_16x16x32_bf16 v[18:21], v[150:153], v[228:231], v[18:21]
	v_mfma_f32_16x16x32_bf16 v[14:17], v[158:161], v[228:231], v[14:17]
	v_mfma_f32_16x16x32_bf16 v[66:69], v[154:157], v[186:189], v[66:69]
	v_mfma_f32_16x16x32_bf16 v[62:65], v[162:165], v[186:189], v[62:65]
	v_mfma_f32_16x16x32_bf16 v[50:53], v[154:157], v[194:197], v[50:53]
	v_mfma_f32_16x16x32_bf16 v[46:49], v[162:165], v[194:197], v[46:49]
	v_mfma_f32_16x16x32_bf16 v[34:37], v[154:157], v[224:227], v[34:37]
	v_mfma_f32_16x16x32_bf16 v[30:33], v[162:165], v[224:227], v[30:33]
	v_mfma_f32_16x16x32_bf16 v[18:21], v[154:157], v[232:235], v[18:21]
	v_mfma_f32_16x16x32_bf16 v[14:17], v[162:165], v[232:235], v[14:17]
	s_setprio 0
	s_setprio 1
	s_add_u32 s46, s46, 0x100
	s_addc_u32 s47, s47, 0
	s_add_u32 s65, s65, 0x100
	s_addc_u32 s66, s66, 0
	v_mfma_f32_16x16x32_bf16 v[58:61], v[166:169], v[182:185], v[58:61]
	v_mfma_f32_16x16x32_bf16 v[54:57], v[174:177], v[182:185], v[54:57]
	v_mfma_f32_16x16x32_bf16 v[42:45], v[166:169], v[190:193], v[42:45]
	v_mfma_f32_16x16x32_bf16 v[38:41], v[174:177], v[190:193], v[38:41]
	v_mfma_f32_16x16x32_bf16 v[26:29], v[166:169], v[206:209], v[26:29]
	v_mfma_f32_16x16x32_bf16 v[22:25], v[174:177], v[206:209], v[22:25]
	v_mfma_f32_16x16x32_bf16 v[8:11], v[166:169], v[228:231], v[10:13]
	v_mfma_f32_16x16x32_bf16 v[4:7], v[174:177], v[228:231], v[4:7]
	v_mfma_f32_16x16x32_bf16 v[58:61], v[170:173], v[186:189], v[58:61]
	v_mfma_f32_16x16x32_bf16 v[54:57], v[178:181], v[186:189], v[54:57]
	v_mfma_f32_16x16x32_bf16 v[42:45], v[170:173], v[194:197], v[42:45]
	v_mfma_f32_16x16x32_bf16 v[38:41], v[178:181], v[194:197], v[38:41]
	v_mfma_f32_16x16x32_bf16 v[26:29], v[170:173], v[224:227], v[26:29]
	v_mfma_f32_16x16x32_bf16 v[22:25], v[178:181], v[224:227], v[22:25]
	v_mfma_f32_16x16x32_bf16 v[10:13], v[170:173], v[232:235], v[8:11]
	v_mfma_f32_16x16x32_bf16 v[6:9], v[178:181], v[232:235], v[4:7]
	s_setprio 0
	s_barrier
	s_cmp_ge_i32 s67, s56
	s_mov_b32 s48, s67
	s_cbranch_scc0 .LBB0_1311
	s_add_i32 s50, s37, 0x1c000
	s_mov_b32 s68, 0x18000
	s_mov_b32 s69, 0x1c000
	s_add_i32 s70, s37, 0x14000

; #define PG8_STAGE(bufoff, gbase, voff) do { _Pragma("unroll") for (int _i = 0; _i < 2; ++_i) \
;         __builtin_amdgcn_global_load_lds((const unsigned*)((const char*)(gbase) + (voff)[_i]), (LAS unsigned*)(lds + (bufoff) + ldsw + _i * 8192), 16, 0, 0); } while (0)
; #define PG8_LDA(dst, b, h) do { _Pragma("unroll") for (int m = 0; m < 4; ++m) _Pragma("unroll") for (int k = 0; k < 2; ++k) dst[m][k] = *(const LAS bf16x8*)(lds + PG8_SA(b, h) + aoff + m * 2048 + k * 1024); } while (0)
; #define PG8_LDB(dst, b, h) do { _Pragma("unroll") for (int n = 0; n < 2; ++n) _Pragma("unroll") for (int k = 0; k < 2; ++k) dst[n][k] = *(const LAS bf16x8*)(lds + PG8_SB(b, h) + boff + n * 2048 + k * 1024); } while (0)
; #define PG8_MMA(ai, bj, At, Bt) do { __builtin_amdgcn_s_setprio(1); _Pragma("unroll") for (int m = 0; m < 4; ++m) _Pragma("unroll") for (int n = 0; n < 2; ++n) _Pragma("unroll") for (int k = 0; k < 2; ++k) \
;         acc[ai][bj][m][n] = __builtin_amdgcn_mfma_f32_16x16x32_bf16(Bt[n][k], At[m][k], acc[ai][bj][m][n], 0, 0, 0); __builtin_amdgcn_s_setprio(0); } while (0)
; #define PG8_WAIT_V(n) asm volatile("s_waitcnt vmcnt(" #n ")" ::: "memory")
; #define PG8_WAIT_L(n) asm volatile("s_waitcnt lgkmcnt(" #n ")" ::: "memory")
; #define PG8_BAR __builtin_amdgcn_s_barrier()
; #define PG8_WAIT_RELAX(flag, n) asm volatile("s_cmp_eq_u32 %0, 0\n\ts_cbranch_scc1 .Lrw%=\n\ts_waitcnt vmcnt(8)\n.Lrw%=:\n\ts_waitcnt vmcnt(%1)" :: "s"(flag), "n"(n) : "scc", "memory")
; #define PG8_SCHED __builtin_amdgcn_sched_barrier(0)
; template <class Epi, bool ALIGN_EPI = true>
; __device__ __forceinline__ void gemm_phase(LAS unsigned char* lds, const Gemm g, const Sched& S, const Epi& E) {
;     ...
;             PG8_LDB(B0, 0, 0); PG8_LDB(B1, 0, 1); PG8_SCHED; PG8_LDA(At, 0, 0); PG8_STAGE(PG8_SA(1, 1), a1 + hstepA, voffA);
;             if constexpr (Epi::NSTORES > 0) PG8_WAIT_RELAX(rflag, 8 + Epi::NSTORES); else PG8_WAIT_V(8);
;             PG8_WAIT_L(0); PG8_BAR; PG8_MMA(0, 0, At, B0); PG8_MMA(0, 1, At, B1); PG8_BAR; PG8_SCHED;
;             PG8_LDA(At, 0, 1); PG8_STAGE(PG8_SB(0, 0), b2, voffB); PG8_STAGE(PG8_SB(0, 1), b2 + hstepB, voffB); PG8_STAGE(PG8_SA(0, 0), a2, voffA);
;             if constexpr (Epi::NSTORES > 0) PG8_WAIT_RELAX(rflag, 8 + Epi::NSTORES); else PG8_WAIT_V(8);
;             PG8_WAIT_L(0); PG8_BAR; PG8_MMA(1, 0, At, B0); PG8_MMA(1, 1, At, B1); PG8_BAR; PG8_SCHED;
.LBB0_1402:
	s_add_i32 s67, s46, 2
	s_add_u32 s47, s44, 0xfff80080
	s_addc_u32 s48, s45, -1
	s_cmp_eq_u32 s59, s46
	s_cselect_b32 s49, s19, s48
	s_cselect_b32 s48, s21, s47
	s_cselect_b32 s47, s63, s66
	s_cselect_b32 s46, s64, s65
	s_add_u32 s100, s44, 0xfff80000
	s_addc_u32 s101, s45, -1
	ds_read_b128 v[150:153], v147
	ds_read_b128 v[154:157], v147 offset:1024
	ds_read_b128 v[158:161], v147 offset:2048
	ds_read_b128 v[162:165], v147 offset:3072
	ds_read_b128 v[166:169], v147 offset:16384
	ds_read_b128 v[170:173], v147 offset:17408
	ds_read_b128 v[174:177], v147 offset:18432
	ds_read_b128 v[178:181], v147 offset:19456
	ds_read_b128 v[182:185], v148
	ds_read_b128 v[186:189], v148 offset:1024
	ds_read_b128 v[190:193], v148 offset:2048
	ds_read_b128 v[194:197], v148 offset:3072
	s_mov_b32 m0, s57
	ds_read_b128 v[206:209], v148 offset:4096
	global_load_lds_dwordx4 v142, s[100:101]
	s_mov_b32 m0, s58
	ds_read_b128 v[224:227], v148 offset:5120
	global_load_lds_dwordx4 v144, s[100:101]
	s_add_i32 m0, s52, 0xc000
	ds_read_b128 v[228:231], v148 offset:6144
	global_load_lds_dwordx4 v142, s[44:45]
	s_add_i32 m0, s52, 0xe000
	ds_read_b128 v[232:235], v148 offset:7168
	global_load_lds_dwordx4 v144, s[44:45]
	s_waitcnt vmcnt(8) lgkmcnt(0)
	s_barrier
	s_setprio 1
	v_mfma_f32_16x16x32_bf16 v[130:133], v[150:153], v[182:185], v[130:133]
	v_mfma_f32_16x16x32_bf16 v[126:129], v[158:161], v[182:185], v[126:129]
	v_mfma_f32_16x16x32_bf16 v[114:117], v[150:153], v[190:193], v[114:117]
	v_mfma_f32_16x16x32_bf16 v[110:113], v[158:161], v[190:193], v[110:113]
	v_mfma_f32_16x16x32_bf16 v[98:101], v[150:153], v[206:209], v[98:101]
	v_mfma_f32_16x16x32_bf16 v[94:97], v[158:161], v[206:209], v[94:97]
	v_mfma_f32_16x16x32_bf16 v[82:85], v[150:153], v[228:231], v[82:85]
	v_mfma_f32_16x16x32_bf16 v[78:81], v[158:161], v[228:231], v[78:81]
	v_mfma_f32_16x16x32_bf16 v[130:133], v[154:157], v[186:189], v[130:133]
	v_mfma_f32_16x16x32_bf16 v[126:129], v[162:165], v[186:189], v[126:129]
	v_mfma_f32_16x16x32_bf16 v[114:117], v[154:157], v[194:197], v[114:117]
	v_mfma_f32_16x16x32_bf16 v[110:113], v[162:165], v[194:197], v[110:113]
	v_mfma_f32_16x16x32_bf16 v[98:101], v[154:157], v[224:227], v[98:101]
	v_mfma_f32_16x16x32_bf16 v[94:97], v[162:165], v[224:227], v[94:97]
	v_mfma_f32_16x16x32_bf16 v[82:85], v[154:157], v[232:235], v[82:85]
	v_mfma_f32_16x16x32_bf16 v[78:81], v[162:165], v[232:235], v[78:81]
	s_setprio 0
	s_setprio 1
	v_mfma_f32_16x16x32_bf16 v[122:125], v[166:169], v[182:185], v[122:125]
	v_mfma_f32_16x16x32_bf16 v[118:121], v[174:177], v[182:185], v[118:121]
	v_mfma_f32_16x16x32_bf16 v[106:109], v[166:169], v[190:193], v[106:109]
	v_mfma_f32_16x16x32_bf16 v[102:105], v[174:177], v[190:193], v[102:105]
	v_mfma_f32_16x16x32_bf16 v[90:93], v[166:169], v[206:209], v[90:93]
	v_mfma_f32_16x16x32_bf16 v[86:89], v[174:177], v[206:209], v[86:89]
	v_mfma_f32_16x16x32_bf16 v[74:77], v[166:169], v[228:231], v[74:77]
	v_mfma_f32_16x16x32_bf16 v[70:73], v[174:177], v[228:231], v[70:73]
	v_mfma_f32_16x16x32_bf16 v[122:125], v[170:173], v[186:189], v[122:125]
	v_mfma_f32_16x16x32_bf16 v[118:121], v[178:181], v[186:189], v[118:121]
	v_mfma_f32_16x16x32_bf16 v[106:109], v[170:173], v[194:197], v[106:109]
	v_mfma_f32_16x16x32_bf16 v[102:105], v[178:181], v[194:197], v[102:105]
	v_mfma_f32_16x16x32_bf16 v[90:93], v[170:173], v[224:227], v[90:93]
	v_mfma_f32_16x16x32_bf16 v[86:89], v[178:181], v[224:227], v[86:89]
	v_mfma_f32_16x16x32_bf16 v[74:77], v[170:173], v[232:235], v[74:77]
	v_mfma_f32_16x16x32_bf16 v[70:73], v[178:181], v[232:235], v[70:73]
	s_setprio 0
	s_barrier
	s_add_u32 s68, s46, 0x80000
	s_addc_u32 s69, s47, 0
	ds_read_b128 v[182:185], v148 offset:16384
	ds_read_b128 v[186:189], v148 offset:17408
	ds_read_b128 v[190:193], v148 offset:18432
	ds_read_b128 v[194:197], v148 offset:19456
	s_add_i32 m0, s51, 0x10000
	ds_read_b128 v[206:209], v148 offset:20480
	global_load_lds_dwordx4 v138, s[46:47]
	s_add_i32 m0, s51, 0x12000
	ds_read_b128 v[224:227], v148 offset:21504
	global_load_lds_dwordx4 v134, s[46:47]
	s_add_i32 m0, s51, 0x14000
	ds_read_b128 v[228:231], v148 offset:22528
	global_load_lds_dwordx4 v138, s[68:69]
	s_add_i32 m0, s51, 0x16000
	ds_read_b128 v[232:235], v148 offset:23552
	global_load_lds_dwordx4 v134, s[68:69]
	s_waitcnt vmcnt(6) lgkmcnt(0)
	s_barrier
	s_setprio 1
	v_mfma_f32_16x16x32_bf16 v[66:69], v[150:153], v[182:185], v[66:69]
	v_mfma_f32_16x16x32_bf16 v[62:65], v[158:161], v[182:185], v[62:65]
	v_mfma_f32_16x16x32_bf16 v[50:53], v[150:153], v[190:193], v[50:53]
	v_mfma_f32_16x16x32_bf16 v[46:49], v[158:161], v[190:193], v[46:49]
	v_mfma_f32_16x16x32_bf16 v[34:37], v[150:153], v[206:209], v[34:37]
	v_mfma_f32_16x16x32_bf16 v[30:33], v[158:161], v[206:209], v[30:33]
	v_mfma_f32_16x16x32_bf16 v[18:21], v[150:153], v[228:231], v[18:21]
	v_mfma_f32_16x16x32_bf16 v[14:17], v[158:161], v[228:231], v[14:17]
	v_mfma_f32_16x16x32_bf16 v[66:69], v[154:157], v[186:189], v[66:69]
	v_mfma_f32_16x16x32_bf16 v[62:65], v[162:165], v[186:189], v[62:65]
	v_mfma_f32_16x16x32_bf16 v[50:53], v[154:157], v[194:197], v[50:53]
	v_mfma_f32_16x16x32_bf16 v[46:49], v[162:165], v[194:197], v[46:49]
	v_mfma_f32_16x16x32_bf16 v[34:37], v[154:157], v[224:227], v[34:37]
	v_mfma_f32_16x16x32_bf16 v[30:33], v[162:165], v[224:227], v[30:33]
	v_mfma_f32_16x16x32_bf16 v[18:21], v[154:157], v[232:235], v[18:21]
	v_mfma_f32_16x16x32_bf16 v[14:17], v[162:165], v[232:235], v[14:17]
	s_setprio 0
	s_setprio 1
	v_mfma_f32_16x16x32_bf16 v[58:61], v[166:169], v[182:185], v[58:61]
	v_mfma_f32_16x16x32_bf16 v[54:57], v[174:177], v[182:185], v[54:57]
	v_mfma_f32_16x16x32_bf16 v[42:45], v[166:169], v[190:193], v[42:45]
	v_mfma_f32_16x16x32_bf16 v[38:41], v[174:177], v[190:193], v[38:41]
	v_mfma_f32_16x16x32_bf16 v[26:29], v[166:169], v[206:209], v[26:29]
	v_mfma_f32_16x16x32_bf16 v[22:25], v[174:177], v[206:209], v[22:25]
	v_mfma_f32_16x16x32_bf16 v[10:13], v[166:169], v[228:231], v[10:13]
	v_mfma_f32_16x16x32_bf16 v[4:7], v[174:177], v[228:231], v[6:9]
	v_mfma_f32_16x16x32_bf16 v[58:61], v[170:173], v[186:189], v[58:61]
	v_mfma_f32_16x16x32_bf16 v[54:57], v[178:181], v[186:189], v[54:57]
	v_mfma_f32_16x16x32_bf16 v[42:45], v[170:173], v[194:197], v[42:45]
	v_mfma_f32_16x16x32_bf16 v[38:41], v[178:181], v[194:197], v[38:41]
	v_mfma_f32_16x16x32_bf16 v[26:29], v[170:173], v[224:227], v[26:29]
	v_mfma_f32_16x16x32_bf16 v[22:25], v[178:181], v[224:227], v[22:25]
	v_mfma_f32_16x16x32_bf16 v[10:13], v[170:173], v[232:235], v[10:13]
	v_mfma_f32_16x16x32_bf16 v[4:7], v[178:181], v[232:235], v[4:7]
	s_setprio 0
	s_barrier
; #define PG8_STAGE(bufoff, gbase, voff) do { _Pragma("unroll") for (int _i = 0; _i < 2; ++_i) \
;         __builtin_amdgcn_global_load_lds((const unsigned*)((const char*)(gbase) + (voff)[_i]), (LAS unsigned*)(lds + (bufoff) + ldsw + _i * 8192), 16, 0, 0); } while (0)
; #define PG8_LDA(dst, b, h) do { _Pragma("unroll") for (int m = 0; m < 4; ++m) _Pragma("unroll") for (int k = 0; k < 2; ++k) dst[m][k] = *(const LAS bf16x8*)(lds + PG8_SA(b, h) + aoff + m * 2048 + k * 1024); } while (0)
; #define PG8_LDB(dst, b, h) do { _Pragma("unroll") for (int n = 0; n < 2; ++n) _Pragma("unroll") for (int k = 0; k < 2; ++k) dst[n][k] = *(const LAS bf16x8*)(lds + PG8_SB(b, h) + boff + n * 2048 + k * 1024); } while (0)
; #define PG8_MMA(ai, bj, At, Bt) do { __builtin_amdgcn_s_setprio(1); _Pragma("unroll") for (int m = 0; m < 4; ++m) _Pragma("unroll") for (int n = 0; n < 2; ++n) _Pragma("unroll") for (int k = 0; k < 2; ++k) \
;         acc[ai][bj][m][n] = __builtin_amdgcn_mfma_f32_16x16x32_bf16(Bt[n][k], At[m][k], acc[ai][bj][m][n], 0, 0, 0); __builtin_amdgcn_s_setprio(0); } while (0)
; #define PG8_WAIT_V(n) asm volatile("s_waitcnt vmcnt(" #n ")" ::: "memory")
; #define PG8_WAIT_L(n) asm volatile("s_waitcnt lgkmcnt(" #n ")" ::: "memory")
; #define PG8_BAR __builtin_amdgcn_s_barrier()
; #define PG8_SCHED __builtin_amdgcn_sched_barrier(0)
; template <class Epi, bool ALIGN_EPI = true>
; __device__ __forceinline__ void gemm_phase(LAS unsigned char* lds, const Gemm g, const Sched& S, const Epi& E) {
;     ...
;             PG8_LDB(B0, 1, 0); PG8_LDB(B1, 1, 1); PG8_SCHED; PG8_LDA(At, 1, 0); PG8_STAGE(PG8_SA(0, 1), a2 + hstepA, voffA);
;             PG8_WAIT_V(8); PG8_WAIT_L(0); PG8_BAR; PG8_MMA(0, 0, At, B0); PG8_MMA(0, 1, At, B1); PG8_BAR; PG8_SCHED;
;             PG8_LDA(At, 1, 1); PG8_STAGE(PG8_SB(1, 0), b3, voffB); PG8_STAGE(PG8_SB(1, 1), b3 + hstepB, voffB); PG8_STAGE(PG8_SA(1, 0), a3, voffA);
;             PG8_WAIT_V(8); PG8_WAIT_L(0); PG8_BAR; PG8_MMA(1, 0, At, B0); PG8_MMA(1, 1, At, B1); PG8_BAR; PG8_SCHED;
	s_mov_b64 s[100:101], s[48:49]
	s_add_u32 s48, s48, 0x80000
	s_addc_u32 s49, s49, 0
	ds_read_b128 v[150:153], v147 offset:32768
	ds_read_b128 v[154:157], v147 offset:33792
	ds_read_b128 v[158:161], v147 offset:34816
	ds_read_b128 v[162:165], v147 offset:35840
	ds_read_b128 v[166:169], v147 offset:49152
	ds_read_b128 v[170:173], v147 offset:50176
	ds_read_b128 v[174:177], v147 offset:51200
	ds_read_b128 v[178:181], v147 offset:52224
	ds_read_b128 v[182:185], v148 offset:32768
	ds_read_b128 v[186:189], v148 offset:33792
	ds_read_b128 v[190:193], v148 offset:34816
	ds_read_b128 v[194:197], v148 offset:35840
	s_mov_b32 m0, s52
	ds_read_b128 v[206:209], v148 offset:36864
	global_load_lds_dwordx4 v140, s[100:101]
	s_mov_b32 m0, s53
	ds_read_b128 v[224:227], v148 offset:37888
	global_load_lds_dwordx4 v136, s[100:101]
	s_mov_b32 m0, s54
	ds_read_b128 v[228:231], v148 offset:38912
	global_load_lds_dwordx4 v140, s[48:49]
	s_mov_b32 m0, s55
	ds_read_b128 v[232:235], v148 offset:39936
	global_load_lds_dwordx4 v136, s[48:49]
	s_waitcnt vmcnt(8) lgkmcnt(0)
	s_barrier
	s_setprio 1
	v_mfma_f32_16x16x32_bf16 v[130:133], v[150:153], v[182:185], v[130:133]
	v_mfma_f32_16x16x32_bf16 v[126:129], v[158:161], v[182:185], v[126:129]
	v_mfma_f32_16x16x32_bf16 v[114:117], v[150:153], v[190:193], v[114:117]
	v_mfma_f32_16x16x32_bf16 v[110:113], v[158:161], v[190:193], v[110:113]
	v_mfma_f32_16x16x32_bf16 v[98:101], v[150:153], v[206:209], v[98:101]
	v_mfma_f32_16x16x32_bf16 v[94:97], v[158:161], v[206:209], v[94:97]
	v_mfma_f32_16x16x32_bf16 v[82:85], v[150:153], v[228:231], v[82:85]
	v_mfma_f32_16x16x32_bf16 v[78:81], v[158:161], v[228:231], v[78:81]
	v_mfma_f32_16x16x32_bf16 v[130:133], v[154:157], v[186:189], v[130:133]
	v_mfma_f32_16x16x32_bf16 v[126:129], v[162:165], v[186:189], v[126:129]
	v_mfma_f32_16x16x32_bf16 v[114:117], v[154:157], v[194:197], v[114:117]
	v_mfma_f32_16x16x32_bf16 v[110:113], v[162:165], v[194:197], v[110:113]
	v_mfma_f32_16x16x32_bf16 v[98:101], v[154:157], v[224:227], v[98:101]
	v_mfma_f32_16x16x32_bf16 v[94:97], v[162:165], v[224:227], v[94:97]
	v_mfma_f32_16x16x32_bf16 v[82:85], v[154:157], v[232:235], v[82:85]
	v_mfma_f32_16x16x32_bf16 v[78:81], v[162:165], v[232:235], v[78:81]
	s_setprio 0
	s_setprio 1
	v_mfma_f32_16x16x32_bf16 v[122:125], v[166:169], v[182:185], v[122:125]
	v_mfma_f32_16x16x32_bf16 v[118:121], v[174:177], v[182:185], v[118:121]
	v_mfma_f32_16x16x32_bf16 v[106:109], v[166:169], v[190:193], v[106:109]
	v_mfma_f32_16x16x32_bf16 v[102:105], v[174:177], v[190:193], v[102:105]
	v_mfma_f32_16x16x32_bf16 v[90:93], v[166:169], v[206:209], v[90:93]
	v_mfma_f32_16x16x32_bf16 v[86:89], v[174:177], v[206:209], v[86:89]
	v_mfma_f32_16x16x32_bf16 v[74:77], v[166:169], v[228:231], v[74:77]
	v_mfma_f32_16x16x32_bf16 v[70:73], v[174:177], v[228:231], v[70:73]
	v_mfma_f32_16x16x32_bf16 v[122:125], v[170:173], v[186:189], v[122:125]
	v_mfma_f32_16x16x32_bf16 v[118:121], v[178:181], v[186:189], v[118:121]
	v_mfma_f32_16x16x32_bf16 v[106:109], v[170:173], v[194:197], v[106:109]
	v_mfma_f32_16x16x32_bf16 v[102:105], v[178:181], v[194:197], v[102:105]
	v_mfma_f32_16x16x32_bf16 v[90:93], v[170:173], v[224:227], v[90:93]
	v_mfma_f32_16x16x32_bf16 v[86:89], v[178:181], v[224:227], v[86:89]
	v_mfma_f32_16x16x32_bf16 v[74:77], v[170:173], v[232:235], v[74:77]
	v_mfma_f32_16x16x32_bf16 v[70:73], v[178:181], v[232:235], v[70:73]
	s_setprio 0
	s_barrier
	ds_read_b128 v[182:185], v148 offset:49152
	ds_read_b128 v[186:189], v148 offset:50176
	ds_read_b128 v[190:193], v148 offset:51200
	ds_read_b128 v[194:197], v148 offset:52224
	s_add_i32 m0, s51, 0x17f80
	ds_read_b128 v[206:209], v148 offset:53248
	global_load_lds_dwordx4 v138, s[46:47] offset:128
	s_add_i32 m0, s51, 0x19f80
	ds_read_b128 v[224:227], v148 offset:54272
	global_load_lds_dwordx4 v134, s[46:47] offset:128
	s_add_i32 m0, s51, 0x1c000
	s_add_u32 s46, s46, 0x80080
	s_addc_u32 s47, s47, 0
	ds_read_b128 v[228:231], v148 offset:55296
	global_load_lds_dwordx4 v138, s[46:47]
	s_add_i32 m0, s51, 0x1e000
	ds_read_b128 v[232:235], v148 offset:56320
	global_load_lds_dwordx4 v134, s[46:47]
	s_waitcnt vmcnt(6) lgkmcnt(0)
	s_barrier
	s_setprio 1
	v_mfma_f32_16x16x32_bf16 v[66:69], v[150:153], v[182:185], v[66:69]
	v_mfma_f32_16x16x32_bf16 v[62:65], v[158:161], v[182:185], v[62:65]
	v_mfma_f32_16x16x32_bf16 v[50:53], v[150:153], v[190:193], v[50:53]
	v_mfma_f32_16x16x32_bf16 v[46:49], v[158:161], v[190:193], v[46:49]
	v_mfma_f32_16x16x32_bf16 v[34:37], v[150:153], v[206:209], v[34:37]
	v_mfma_f32_16x16x32_bf16 v[30:33], v[158:161], v[206:209], v[30:33]
	v_mfma_f32_16x16x32_bf16 v[18:21], v[150:153], v[228:231], v[18:21]
	v_mfma_f32_16x16x32_bf16 v[14:17], v[158:161], v[228:231], v[14:17]
	v_mfma_f32_16x16x32_bf16 v[66:69], v[154:157], v[186:189], v[66:69]
	v_mfma_f32_16x16x32_bf16 v[62:65], v[162:165], v[186:189], v[62:65]
	v_mfma_f32_16x16x32_bf16 v[50:53], v[154:157], v[194:197], v[50:53]
	v_mfma_f32_16x16x32_bf16 v[46:49], v[162:165], v[194:197], v[46:49]
	v_mfma_f32_16x16x32_bf16 v[34:37], v[154:157], v[224:227], v[34:37]
	v_mfma_f32_16x16x32_bf16 v[30:33], v[162:165], v[224:227], v[30:33]
	v_mfma_f32_16x16x32_bf16 v[18:21], v[154:157], v[232:235], v[18:21]
	v_mfma_f32_16x16x32_bf16 v[14:17], v[162:165], v[232:235], v[14:17]
	s_setprio 0
	s_setprio 1
	s_add_u32 s44, s44, 0x100
	s_addc_u32 s45, s45, 0
	s_add_u32 s65, s65, 0x100
	s_addc_u32 s66, s66, 0
	v_mfma_f32_16x16x32_bf16 v[58:61], v[166:169], v[182:185], v[58:61]
	v_mfma_f32_16x16x32_bf16 v[54:57], v[174:177], v[182:185], v[54:57]
	v_mfma_f32_16x16x32_bf16 v[42:45], v[166:169], v[190:193], v[42:45]
	v_mfma_f32_16x16x32_bf16 v[38:41], v[174:177], v[190:193], v[38:41]
	v_mfma_f32_16x16x32_bf16 v[26:29], v[166:169], v[206:209], v[26:29]
	v_mfma_f32_16x16x32_bf16 v[22:25], v[174:177], v[206:209], v[22:25]
	v_mfma_f32_16x16x32_bf16 v[8:11], v[166:169], v[228:231], v[10:13]
	v_mfma_f32_16x16x32_bf16 v[4:7], v[174:177], v[228:231], v[4:7]
	v_mfma_f32_16x16x32_bf16 v[58:61], v[170:173], v[186:189], v[58:61]
	v_mfma_f32_16x16x32_bf16 v[54:57], v[178:181], v[186:189], v[54:57]
	v_mfma_f32_16x16x32_bf16 v[42:45], v[170:173], v[194:197], v[42:45]
	v_mfma_f32_16x16x32_bf16 v[38:41], v[178:181], v[194:197], v[38:41]
	v_mfma_f32_16x16x32_bf16 v[26:29], v[170:173], v[224:227], v[26:29]
	v_mfma_f32_16x16x32_bf16 v[22:25], v[178:181], v[224:227], v[22:25]
	v_mfma_f32_16x16x32_bf16 v[10:13], v[170:173], v[232:235], v[8:11]
	v_mfma_f32_16x16x32_bf16 v[6:9], v[178:181], v[232:235], v[4:7]
	s_setprio 0
	s_barrier
	s_cmp_ge_i32 s67, s56
	s_mov_b32 s46, s67
	s_cbranch_scc0 .LBB0_1402
	s_add_i32 s48, s51, 0x1c000
	s_mov_b32 s68, 0x18000
	s_mov_b32 s69, 0x1c000
	s_add_i32 s70, s51, 0x14000

; #define PG8_STAGE(bufoff, gbase, voff) do { _Pragma("unroll") for (int _i = 0; _i < 2; ++_i) \
;         __builtin_amdgcn_global_load_lds((const unsigned*)((const char*)(gbase) + (voff)[_i]), (LAS unsigned*)(lds + (bufoff) + ldsw + _i * 8192), 16, 0, 0); } while (0)
; #define PG8_LDA(dst, b, h) do { _Pragma("unroll") for (int m = 0; m < 4; ++m) _Pragma("unroll") for (int k = 0; k < 2; ++k) dst[m][k] = *(const LAS bf16x8*)(lds + PG8_SA(b, h) + aoff + m * 2048 + k * 1024); } while (0)
; #define PG8_LDB(dst, b, h) do { _Pragma("unroll") for (int n = 0; n < 2; ++n) _Pragma("unroll") for (int k = 0; k < 2; ++k) dst[n][k] = *(const LAS bf16x8*)(lds + PG8_SB(b, h) + boff + n * 2048 + k * 1024); } while (0)
; #define PG8_MMA(ai, bj, At, Bt) do { __builtin_amdgcn_s_setprio(1); _Pragma("unroll") for (int m = 0; m < 4; ++m) _Pragma("unroll") for (int n = 0; n < 2; ++n) _Pragma("unroll") for (int k = 0; k < 2; ++k) \
;         acc[ai][bj][m][n] = __builtin_amdgcn_mfma_f32_16x16x32_bf16(Bt[n][k], At[m][k], acc[ai][bj][m][n], 0, 0, 0); __builtin_amdgcn_s_setprio(0); } while (0)
; #define PG8_WAIT_V(n) asm volatile("s_waitcnt vmcnt(" #n ")" ::: "memory")
; #define PG8_WAIT_L(n) asm volatile("s_waitcnt lgkmcnt(" #n ")" ::: "memory")
; #define PG8_BAR __builtin_amdgcn_s_barrier()
; #define PG8_WAIT_RELAX(flag, n) asm volatile("s_cmp_eq_u32 %0, 0\n\ts_cbranch_scc1 .Lrw%=\n\ts_waitcnt vmcnt(8)\n.Lrw%=:\n\ts_waitcnt vmcnt(%1)" :: "s"(flag), "n"(n) : "scc", "memory")
; #define PG8_SCHED __builtin_amdgcn_sched_barrier(0)
; template <class Epi, bool ALIGN_EPI = true>
; __device__ __forceinline__ void gemm_phase(LAS unsigned char* lds, const Gemm g, const Sched& S, const Epi& E) {
;     ...
;             PG8_LDB(B0, 0, 0); PG8_LDB(B1, 0, 1); PG8_SCHED; PG8_LDA(At, 0, 0); PG8_STAGE(PG8_SA(1, 1), a1 + hstepA, voffA);
;             if constexpr (Epi::NSTORES > 0) PG8_WAIT_RELAX(rflag, 8 + Epi::NSTORES); else PG8_WAIT_V(8);
;             PG8_WAIT_L(0); PG8_BAR; PG8_MMA(0, 0, At, B0); PG8_MMA(0, 1, At, B1); PG8_BAR; PG8_SCHED;
;             PG8_LDA(At, 0, 1); PG8_STAGE(PG8_SB(0, 0), b2, voffB); PG8_STAGE(PG8_SB(0, 1), b2 + hstepB, voffB); PG8_STAGE(PG8_SA(0, 0), a2, voffA);
;             if constexpr (Epi::NSTORES > 0) PG8_WAIT_RELAX(rflag, 8 + Epi::NSTORES); else PG8_WAIT_V(8);
;             PG8_WAIT_L(0); PG8_BAR; PG8_MMA(1, 0, At, B0); PG8_MMA(1, 1, At, B1); PG8_BAR; PG8_SCHED;
.LBB0_1929:
	s_add_i32 s67, s48, 2
	s_add_u32 s49, s46, 0xfffc0080
	s_addc_u32 s50, s47, -1
	s_cmp_eq_u32 s59, s48
	s_cselect_b32 s51, s21, s50
	s_cselect_b32 s50, s23, s49
	s_cselect_b32 s49, s63, s66
	s_cselect_b32 s48, s64, s65
	s_add_u32 s100, s46, 0xfffc0000
	s_addc_u32 s101, s47, -1
	ds_read_b128 v[150:153], v147
	ds_read_b128 v[154:157], v147 offset:1024
	ds_read_b128 v[158:161], v147 offset:2048
	ds_read_b128 v[162:165], v147 offset:3072
	ds_read_b128 v[166:169], v147 offset:16384
	ds_read_b128 v[170:173], v147 offset:17408
	ds_read_b128 v[174:177], v147 offset:18432
	ds_read_b128 v[178:181], v147 offset:19456
	ds_read_b128 v[182:185], v148
	ds_read_b128 v[186:189], v148 offset:1024
	ds_read_b128 v[190:193], v148 offset:2048
	ds_read_b128 v[194:197], v148 offset:3072
	s_mov_b32 m0, s57
	ds_read_b128 v[206:209], v148 offset:4096
	global_load_lds_dwordx4 v142, s[100:101]
	s_mov_b32 m0, s58
	ds_read_b128 v[224:227], v148 offset:5120
	global_load_lds_dwordx4 v144, s[100:101]
	s_add_i32 m0, s52, 0xc000
	ds_read_b128 v[228:231], v148 offset:6144
	global_load_lds_dwordx4 v142, s[46:47]
	s_add_i32 m0, s52, 0xe000
	ds_read_b128 v[232:235], v148 offset:7168
	global_load_lds_dwordx4 v144, s[46:47]
	s_waitcnt vmcnt(8) lgkmcnt(0)
	s_barrier
	s_setprio 1
	v_mfma_f32_16x16x32_bf16 v[130:133], v[150:153], v[182:185], v[130:133]
	v_mfma_f32_16x16x32_bf16 v[126:129], v[158:161], v[182:185], v[126:129]
	v_mfma_f32_16x16x32_bf16 v[114:117], v[150:153], v[190:193], v[114:117]
	v_mfma_f32_16x16x32_bf16 v[110:113], v[158:161], v[190:193], v[110:113]
	v_mfma_f32_16x16x32_bf16 v[98:101], v[150:153], v[206:209], v[98:101]
	v_mfma_f32_16x16x32_bf16 v[94:97], v[158:161], v[206:209], v[94:97]
	v_mfma_f32_16x16x32_bf16 v[82:85], v[150:153], v[228:231], v[82:85]
	v_mfma_f32_16x16x32_bf16 v[78:81], v[158:161], v[228:231], v[78:81]
	v_mfma_f32_16x16x32_bf16 v[130:133], v[154:157], v[186:189], v[130:133]
	v_mfma_f32_16x16x32_bf16 v[126:129], v[162:165], v[186:189], v[126:129]
	v_mfma_f32_16x16x32_bf16 v[114:117], v[154:157], v[194:197], v[114:117]
	v_mfma_f32_16x16x32_bf16 v[110:113], v[162:165], v[194:197], v[110:113]
	v_mfma_f32_16x16x32_bf16 v[98:101], v[154:157], v[224:227], v[98:101]
	v_mfma_f32_16x16x32_bf16 v[94:97], v[162:165], v[224:227], v[94:97]
	v_mfma_f32_16x16x32_bf16 v[82:85], v[154:157], v[232:235], v[82:85]
	v_mfma_f32_16x16x32_bf16 v[78:81], v[162:165], v[232:235], v[78:81]
	s_setprio 0
	s_setprio 1
	v_mfma_f32_16x16x32_bf16 v[122:125], v[166:169], v[182:185], v[122:125]
	v_mfma_f32_16x16x32_bf16 v[118:121], v[174:177], v[182:185], v[118:121]
	v_mfma_f32_16x16x32_bf16 v[106:109], v[166:169], v[190:193], v[106:109]
	v_mfma_f32_16x16x32_bf16 v[102:105], v[174:177], v[190:193], v[102:105]
	v_mfma_f32_16x16x32_bf16 v[90:93], v[166:169], v[206:209], v[90:93]
	v_mfma_f32_16x16x32_bf16 v[86:89], v[174:177], v[206:209], v[86:89]
	v_mfma_f32_16x16x32_bf16 v[74:77], v[166:169], v[228:231], v[74:77]
	v_mfma_f32_16x16x32_bf16 v[70:73], v[174:177], v[228:231], v[70:73]
	v_mfma_f32_16x16x32_bf16 v[122:125], v[170:173], v[186:189], v[122:125]
	v_mfma_f32_16x16x32_bf16 v[118:121], v[178:181], v[186:189], v[118:121]
	v_mfma_f32_16x16x32_bf16 v[106:109], v[170:173], v[194:197], v[106:109]
	v_mfma_f32_16x16x32_bf16 v[102:105], v[178:181], v[194:197], v[102:105]
	v_mfma_f32_16x16x32_bf16 v[90:93], v[170:173], v[224:227], v[90:93]
	v_mfma_f32_16x16x32_bf16 v[86:89], v[178:181], v[224:227], v[86:89]
	v_mfma_f32_16x16x32_bf16 v[74:77], v[170:173], v[232:235], v[74:77]
	v_mfma_f32_16x16x32_bf16 v[70:73], v[178:181], v[232:235], v[70:73]
	s_setprio 0
	s_barrier
	s_add_u32 s68, s48, 0x40000
	s_addc_u32 s69, s49, 0
	ds_read_b128 v[182:185], v148 offset:16384
	ds_read_b128 v[186:189], v148 offset:17408
	ds_read_b128 v[190:193], v148 offset:18432
	ds_read_b128 v[194:197], v148 offset:19456
	s_add_i32 m0, s37, 0x10000
	ds_read_b128 v[206:209], v148 offset:20480
	global_load_lds_dwordx4 v138, s[48:49]
	s_add_i32 m0, s37, 0x12000
	ds_read_b128 v[224:227], v148 offset:21504
	global_load_lds_dwordx4 v134, s[48:49]
	s_add_i32 m0, s37, 0x14000
	ds_read_b128 v[228:231], v148 offset:22528
	global_load_lds_dwordx4 v138, s[68:69]
	s_add_i32 m0, s37, 0x16000
	ds_read_b128 v[232:235], v148 offset:23552
	global_load_lds_dwordx4 v134, s[68:69]
	s_waitcnt vmcnt(6) lgkmcnt(0)
	s_barrier
	s_setprio 1
	v_mfma_f32_16x16x32_bf16 v[66:69], v[150:153], v[182:185], v[66:69]
	v_mfma_f32_16x16x32_bf16 v[62:65], v[158:161], v[182:185], v[62:65]
	v_mfma_f32_16x16x32_bf16 v[50:53], v[150:153], v[190:193], v[50:53]
	v_mfma_f32_16x16x32_bf16 v[46:49], v[158:161], v[190:193], v[46:49]
	v_mfma_f32_16x16x32_bf16 v[34:37], v[150:153], v[206:209], v[34:37]
	v_mfma_f32_16x16x32_bf16 v[30:33], v[158:161], v[206:209], v[30:33]
	v_mfma_f32_16x16x32_bf16 v[18:21], v[150:153], v[228:231], v[18:21]
	v_mfma_f32_16x16x32_bf16 v[14:17], v[158:161], v[228:231], v[14:17]
	v_mfma_f32_16x16x32_bf16 v[66:69], v[154:157], v[186:189], v[66:69]
	v_mfma_f32_16x16x32_bf16 v[62:65], v[162:165], v[186:189], v[62:65]
	v_mfma_f32_16x16x32_bf16 v[50:53], v[154:157], v[194:197], v[50:53]
	v_mfma_f32_16x16x32_bf16 v[46:49], v[162:165], v[194:197], v[46:49]
	v_mfma_f32_16x16x32_bf16 v[34:37], v[154:157], v[224:227], v[34:37]
	v_mfma_f32_16x16x32_bf16 v[30:33], v[162:165], v[224:227], v[30:33]
	v_mfma_f32_16x16x32_bf16 v[18:21], v[154:157], v[232:235], v[18:21]
	v_mfma_f32_16x16x32_bf16 v[14:17], v[162:165], v[232:235], v[14:17]
	s_setprio 0
	s_setprio 1
	v_mfma_f32_16x16x32_bf16 v[58:61], v[166:169], v[182:185], v[58:61]
	v_mfma_f32_16x16x32_bf16 v[54:57], v[174:177], v[182:185], v[54:57]
	v_mfma_f32_16x16x32_bf16 v[42:45], v[166:169], v[190:193], v[42:45]
	v_mfma_f32_16x16x32_bf16 v[38:41], v[174:177], v[190:193], v[38:41]
	v_mfma_f32_16x16x32_bf16 v[26:29], v[166:169], v[206:209], v[26:29]
	v_mfma_f32_16x16x32_bf16 v[22:25], v[174:177], v[206:209], v[22:25]
	v_mfma_f32_16x16x32_bf16 v[10:13], v[166:169], v[228:231], v[10:13]
	v_mfma_f32_16x16x32_bf16 v[4:7], v[174:177], v[228:231], v[6:9]
	v_mfma_f32_16x16x32_bf16 v[58:61], v[170:173], v[186:189], v[58:61]
	v_mfma_f32_16x16x32_bf16 v[54:57], v[178:181], v[186:189], v[54:57]
	v_mfma_f32_16x16x32_bf16 v[42:45], v[170:173], v[194:197], v[42:45]
	v_mfma_f32_16x16x32_bf16 v[38:41], v[178:181], v[194:197], v[38:41]
	v_mfma_f32_16x16x32_bf16 v[26:29], v[170:173], v[224:227], v[26:29]
	v_mfma_f32_16x16x32_bf16 v[22:25], v[178:181], v[224:227], v[22:25]
	v_mfma_f32_16x16x32_bf16 v[10:13], v[170:173], v[232:235], v[10:13]
	v_mfma_f32_16x16x32_bf16 v[4:7], v[178:181], v[232:235], v[4:7]
	s_setprio 0
	s_barrier
; #define PG8_STAGE(bufoff, gbase, voff) do { _Pragma("unroll") for (int _i = 0; _i < 2; ++_i) \
;         __builtin_amdgcn_global_load_lds((const unsigned*)((const char*)(gbase) + (voff)[_i]), (LAS unsigned*)(lds + (bufoff) + ldsw + _i * 8192), 16, 0, 0); } while (0)
; #define PG8_LDA(dst, b, h) do { _Pragma("unroll") for (int m = 0; m < 4; ++m) _Pragma("unroll") for (int k = 0; k < 2; ++k) dst[m][k] = *(const LAS bf16x8*)(lds + PG8_SA(b, h) + aoff + m * 2048 + k * 1024); } while (0)
; #define PG8_LDB(dst, b, h) do { _Pragma("unroll") for (int n = 0; n < 2; ++n) _Pragma("unroll") for (int k = 0; k < 2; ++k) dst[n][k] = *(const LAS bf16x8*)(lds + PG8_SB(b, h) + boff + n * 2048 + k * 1024); } while (0)
; #define PG8_MMA(ai, bj, At, Bt) do { __builtin_amdgcn_s_setprio(1); _Pragma("unroll") for (int m = 0; m < 4; ++m) _Pragma("unroll") for (int n = 0; n < 2; ++n) _Pragma("unroll") for (int k = 0; k < 2; ++k) \
;         acc[ai][bj][m][n] = __builtin_amdgcn_mfma_f32_16x16x32_bf16(Bt[n][k], At[m][k], acc[ai][bj][m][n], 0, 0, 0); __builtin_amdgcn_s_setprio(0); } while (0)
; #define PG8_WAIT_V(n) asm volatile("s_waitcnt vmcnt(" #n ")" ::: "memory")
; #define PG8_WAIT_L(n) asm volatile("s_waitcnt lgkmcnt(" #n ")" ::: "memory")
; #define PG8_BAR __builtin_amdgcn_s_barrier()
; #define PG8_SCHED __builtin_amdgcn_sched_barrier(0)
; template <class Epi, bool ALIGN_EPI = true>
; __device__ __forceinline__ void gemm_phase(LAS unsigned char* lds, const Gemm g, const Sched& S, const Epi& E) {
;     ...
;             PG8_LDB(B0, 1, 0); PG8_LDB(B1, 1, 1); PG8_SCHED; PG8_LDA(At, 1, 0); PG8_STAGE(PG8_SA(0, 1), a2 + hstepA, voffA);
;             PG8_WAIT_V(8); PG8_WAIT_L(0); PG8_BAR; PG8_MMA(0, 0, At, B0); PG8_MMA(0, 1, At, B1); PG8_BAR; PG8_SCHED;
;             PG8_LDA(At, 1, 1); PG8_STAGE(PG8_SB(1, 0), b3, voffB); PG8_STAGE(PG8_SB(1, 1), b3 + hstepB, voffB); PG8_STAGE(PG8_SA(1, 0), a3, voffA);
;             PG8_WAIT_V(8); PG8_WAIT_L(0); PG8_BAR; PG8_MMA(1, 0, At, B0); PG8_MMA(1, 1, At, B1); PG8_BAR; PG8_SCHED;
	s_mov_b64 s[100:101], s[50:51]
	s_add_u32 s50, s50, 0x40000
	s_addc_u32 s51, s51, 0
	ds_read_b128 v[150:153], v147 offset:32768
	ds_read_b128 v[154:157], v147 offset:33792
	ds_read_b128 v[158:161], v147 offset:34816
	ds_read_b128 v[162:165], v147 offset:35840
	ds_read_b128 v[166:169], v147 offset:49152
	ds_read_b128 v[170:173], v147 offset:50176
	ds_read_b128 v[174:177], v147 offset:51200
	ds_read_b128 v[178:181], v147 offset:52224
	ds_read_b128 v[182:185], v148 offset:32768
	ds_read_b128 v[186:189], v148 offset:33792
	ds_read_b128 v[190:193], v148 offset:34816
	ds_read_b128 v[194:197], v148 offset:35840
	s_mov_b32 m0, s52
	ds_read_b128 v[206:209], v148 offset:36864
	global_load_lds_dwordx4 v140, s[100:101]
	s_mov_b32 m0, s53
	ds_read_b128 v[224:227], v148 offset:37888
	global_load_lds_dwordx4 v136, s[100:101]
	s_mov_b32 m0, s54
	ds_read_b128 v[228:231], v148 offset:38912
	global_load_lds_dwordx4 v140, s[50:51]
	s_mov_b32 m0, s55
	ds_read_b128 v[232:235], v148 offset:39936
	global_load_lds_dwordx4 v136, s[50:51]
	s_waitcnt vmcnt(8) lgkmcnt(0)
	s_barrier
	s_setprio 1
	v_mfma_f32_16x16x32_bf16 v[130:133], v[150:153], v[182:185], v[130:133]
	v_mfma_f32_16x16x32_bf16 v[126:129], v[158:161], v[182:185], v[126:129]
	v_mfma_f32_16x16x32_bf16 v[114:117], v[150:153], v[190:193], v[114:117]
	v_mfma_f32_16x16x32_bf16 v[110:113], v[158:161], v[190:193], v[110:113]
	v_mfma_f32_16x16x32_bf16 v[98:101], v[150:153], v[206:209], v[98:101]
	v_mfma_f32_16x16x32_bf16 v[94:97], v[158:161], v[206:209], v[94:97]
	v_mfma_f32_16x16x32_bf16 v[82:85], v[150:153], v[228:231], v[82:85]
	v_mfma_f32_16x16x32_bf16 v[78:81], v[158:161], v[228:231], v[78:81]
	v_mfma_f32_16x16x32_bf16 v[130:133], v[154:157], v[186:189], v[130:133]
	v_mfma_f32_16x16x32_bf16 v[126:129], v[162:165], v[186:189], v[126:129]
	v_mfma_f32_16x16x32_bf16 v[114:117], v[154:157], v[194:197], v[114:117]
	v_mfma_f32_16x16x32_bf16 v[110:113], v[162:165], v[194:197], v[110:113]
	v_mfma_f32_16x16x32_bf16 v[98:101], v[154:157], v[224:227], v[98:101]
	v_mfma_f32_16x16x32_bf16 v[94:97], v[162:165], v[224:227], v[94:97]
	v_mfma_f32_16x16x32_bf16 v[82:85], v[154:157], v[232:235], v[82:85]
	v_mfma_f32_16x16x32_bf16 v[78:81], v[162:165], v[232:235], v[78:81]
	s_setprio 0
	s_setprio 1
	v_mfma_f32_16x16x32_bf16 v[122:125], v[166:169], v[182:185], v[122:125]
	v_mfma_f32_16x16x32_bf16 v[118:121], v[174:177], v[182:185], v[118:121]
	v_mfma_f32_16x16x32_bf16 v[106:109], v[166:169], v[190:193], v[106:109]
	v_mfma_f32_16x16x32_bf16 v[102:105], v[174:177], v[190:193], v[102:105]
	v_mfma_f32_16x16x32_bf16 v[90:93], v[166:169], v[206:209], v[90:93]
	v_mfma_f32_16x16x32_bf16 v[86:89], v[174:177], v[206:209], v[86:89]
	v_mfma_f32_16x16x32_bf16 v[74:77], v[166:169], v[228:231], v[74:77]
	v_mfma_f32_16x16x32_bf16 v[70:73], v[174:177], v[228:231], v[70:73]
	v_mfma_f32_16x16x32_bf16 v[122:125], v[170:173], v[186:189], v[122:125]
	v_mfma_f32_16x16x32_bf16 v[118:121], v[178:181], v[186:189], v[118:121]
	v_mfma_f32_16x16x32_bf16 v[106:109], v[170:173], v[194:197], v[106:109]
	v_mfma_f32_16x16x32_bf16 v[102:105], v[178:181], v[194:197], v[102:105]
	v_mfma_f32_16x16x32_bf16 v[90:93], v[170:173], v[224:227], v[90:93]
	v_mfma_f32_16x16x32_bf16 v[86:89], v[178:181], v[224:227], v[86:89]
	v_mfma_f32_16x16x32_bf16 v[74:77], v[170:173], v[232:235], v[74:77]
	v_mfma_f32_16x16x32_bf16 v[70:73], v[178:181], v[232:235], v[70:73]
	s_setprio 0
	s_barrier
	ds_read_b128 v[182:185], v148 offset:49152
	ds_read_b128 v[186:189], v148 offset:50176
	ds_read_b128 v[190:193], v148 offset:51200
	ds_read_b128 v[194:197], v148 offset:52224
	s_add_i32 m0, s37, 0x17f80
	ds_read_b128 v[206:209], v148 offset:53248
	global_load_lds_dwordx4 v138, s[48:49] offset:128
	s_add_i32 m0, s37, 0x19f80
	ds_read_b128 v[224:227], v148 offset:54272
	global_load_lds_dwordx4 v134, s[48:49] offset:128
	s_add_i32 m0, s37, 0x1c000
	s_add_u32 s48, s48, 0x40080
	s_addc_u32 s49, s49, 0
	ds_read_b128 v[228:231], v148 offset:55296
	global_load_lds_dwordx4 v138, s[48:49]
	s_add_i32 m0, s37, 0x1e000
	ds_read_b128 v[232:235], v148 offset:56320
	global_load_lds_dwordx4 v134, s[48:49]
	s_waitcnt vmcnt(6) lgkmcnt(0)
	s_barrier
	s_setprio 1
	v_mfma_f32_16x16x32_bf16 v[66:69], v[150:153], v[182:185], v[66:69]
	v_mfma_f32_16x16x32_bf16 v[62:65], v[158:161], v[182:185], v[62:65]
	v_mfma_f32_16x16x32_bf16 v[50:53], v[150:153], v[190:193], v[50:53]
	v_mfma_f32_16x16x32_bf16 v[46:49], v[158:161], v[190:193], v[46:49]
	v_mfma_f32_16x16x32_bf16 v[34:37], v[150:153], v[206:209], v[34:37]
	v_mfma_f32_16x16x32_bf16 v[30:33], v[158:161], v[206:209], v[30:33]
	v_mfma_f32_16x16x32_bf16 v[18:21], v[150:153], v[228:231], v[18:21]
	v_mfma_f32_16x16x32_bf16 v[14:17], v[158:161], v[228:231], v[14:17]
	v_mfma_f32_16x16x32_bf16 v[66:69], v[154:157], v[186:189], v[66:69]
	v_mfma_f32_16x16x32_bf16 v[62:65], v[162:165], v[186:189], v[62:65]
	v_mfma_f32_16x16x32_bf16 v[50:53], v[154:157], v[194:197], v[50:53]
	v_mfma_f32_16x16x32_bf16 v[46:49], v[162:165], v[194:197], v[46:49]
	v_mfma_f32_16x16x32_bf16 v[34:37], v[154:157], v[224:227], v[34:37]
	v_mfma_f32_16x16x32_bf16 v[30:33], v[162:165], v[224:227], v[30:33]
	v_mfma_f32_16x16x32_bf16 v[18:21], v[154:157], v[232:235], v[18:21]
	v_mfma_f32_16x16x32_bf16 v[14:17], v[162:165], v[232:235], v[14:17]
	s_setprio 0
	s_setprio 1
	s_add_u32 s46, s46, 0x100
	s_addc_u32 s47, s47, 0
	s_add_u32 s65, s65, 0x100
	s_addc_u32 s66, s66, 0
	v_mfma_f32_16x16x32_bf16 v[58:61], v[166:169], v[182:185], v[58:61]
	v_mfma_f32_16x16x32_bf16 v[54:57], v[174:177], v[182:185], v[54:57]
	v_mfma_f32_16x16x32_bf16 v[42:45], v[166:169], v[190:193], v[42:45]
	v_mfma_f32_16x16x32_bf16 v[38:41], v[174:177], v[190:193], v[38:41]
	v_mfma_f32_16x16x32_bf16 v[26:29], v[166:169], v[206:209], v[26:29]
	v_mfma_f32_16x16x32_bf16 v[22:25], v[174:177], v[206:209], v[22:25]
	v_mfma_f32_16x16x32_bf16 v[8:11], v[166:169], v[228:231], v[10:13]
	v_mfma_f32_16x16x32_bf16 v[4:7], v[174:177], v[228:231], v[4:7]
	v_mfma_f32_16x16x32_bf16 v[58:61], v[170:173], v[186:189], v[58:61]
	v_mfma_f32_16x16x32_bf16 v[54:57], v[178:181], v[186:189], v[54:57]
	v_mfma_f32_16x16x32_bf16 v[42:45], v[170:173], v[194:197], v[42:45]
	v_mfma_f32_16x16x32_bf16 v[38:41], v[178:181], v[194:197], v[38:41]
	v_mfma_f32_16x16x32_bf16 v[26:29], v[170:173], v[224:227], v[26:29]
	v_mfma_f32_16x16x32_bf16 v[22:25], v[178:181], v[224:227], v[22:25]
	v_mfma_f32_16x16x32_bf16 v[10:13], v[170:173], v[232:235], v[8:11]
	v_mfma_f32_16x16x32_bf16 v[6:9], v[178:181], v[232:235], v[4:7]
	s_setprio 0
	s_barrier
	s_cmp_ge_i32 s67, s56
	s_mov_b32 s48, s67
	s_cbranch_scc0 .LBB0_1929
	s_add_i32 s50, s37, 0x1c000
	s_mov_b32 s68, 0x18000
	s_mov_b32 s69, 0x1c000
	s_add_i32 s70, s37, 0x14000

; #define PG8_MMA(ai, bj, At, Bt) do { __builtin_amdgcn_s_setprio(1); _Pragma("unroll") for (int m = 0; m < 4; ++m) _Pragma("unroll") for (int n = 0; n < 2; ++n) _Pragma("unroll") for (int k = 0; k < 2; ++k) \
;         acc[ai][bj][m][n] = __builtin_amdgcn_mfma_f32_16x16x32_bf16(Bt[n][k], At[m][k], acc[ai][bj][m][n], 0, 0, 0); __builtin_amdgcn_s_setprio(0); } while (0)
; #define PG8_WAIT_V(n) asm volatile("s_waitcnt vmcnt(" #n ")" ::: "memory")
; #define PG8_WAIT_L(n) asm volatile("s_waitcnt lgkmcnt(" #n ")" ::: "memory")
; #define PG8_BAR __builtin_amdgcn_s_barrier()
; #define PG8_SCHED __builtin_amdgcn_sched_barrier(0)
; template <class Epi, bool ALIGN_EPI = true>
; __device__ __forceinline__ void gemm_phase(LAS unsigned char* lds, const Gemm g, const Sched& S, const Epi& E) {
;     ...
;             PG8_WAIT_V(8); PG8_WAIT_L(0); PG8_BAR; PG8_MMA(1, 0, At, B0); PG8_MMA(1, 1, At, B1); PG8_BAR; PG8_SCHED;
.Lx4last_13:
	s_waitcnt vmcnt(6) lgkmcnt(0)
	s_barrier
	s_setprio 1
	v_mfma_f32_16x16x32_bf16 v[66:69], v[146:149], v[182:185], v[66:69]
	v_mfma_f32_16x16x32_bf16 v[62:65], v[158:161], v[182:185], v[62:65]
	v_mfma_f32_16x16x32_bf16 v[58:61], v[146:149], v[190:193], v[58:61]
	v_mfma_f32_16x16x32_bf16 v[54:57], v[158:161], v[190:193], v[54:57]
	v_mfma_f32_16x16x32_bf16 v[50:53], v[146:149], v[206:209], v[50:53]
	v_mfma_f32_16x16x32_bf16 v[46:49], v[158:161], v[206:209], v[46:49]
	v_mfma_f32_16x16x32_bf16 v[42:45], v[146:149], v[228:231], v[42:45]
	v_mfma_f32_16x16x32_bf16 v[38:41], v[158:161], v[228:231], v[38:41]
	v_mfma_f32_16x16x32_bf16 v[66:69], v[154:157], v[186:189], v[66:69]
	v_mfma_f32_16x16x32_bf16 v[62:65], v[162:165], v[186:189], v[62:65]
	v_mfma_f32_16x16x32_bf16 v[58:61], v[154:157], v[194:197], v[58:61]
	v_mfma_f32_16x16x32_bf16 v[54:57], v[162:165], v[194:197], v[54:57]
	v_mfma_f32_16x16x32_bf16 v[50:53], v[154:157], v[224:227], v[50:53]
	v_mfma_f32_16x16x32_bf16 v[46:49], v[162:165], v[224:227], v[46:49]
	v_mfma_f32_16x16x32_bf16 v[42:45], v[154:157], v[232:235], v[42:45]
	v_mfma_f32_16x16x32_bf16 v[38:41], v[162:165], v[232:235], v[38:41]
	s_setprio 0
	s_setprio 1
	s_add_u32 s26, s26, 0x100
	s_addc_u32 s27, s27, 0
	s_add_u32 s67, s67, 0x100
	s_addc_u32 s68, s68, 0
	v_mfma_f32_16x16x32_bf16 v[34:37], v[166:169], v[182:185], v[34:37]
	v_mfma_f32_16x16x32_bf16 v[30:33], v[174:177], v[182:185], v[30:33]
	v_mfma_f32_16x16x32_bf16 v[26:29], v[166:169], v[190:193], v[26:29]
	v_mfma_f32_16x16x32_bf16 v[22:25], v[174:177], v[190:193], v[22:25]
	v_mfma_f32_16x16x32_bf16 v[18:21], v[166:169], v[206:209], v[18:21]
	v_mfma_f32_16x16x32_bf16 v[14:17], v[174:177], v[206:209], v[14:17]
	v_mfma_f32_16x16x32_bf16 v[8:11], v[166:169], v[228:231], v[10:13]
	v_mfma_f32_16x16x32_bf16 v[4:7], v[174:177], v[228:231], v[4:7]
	v_mfma_f32_16x16x32_bf16 v[34:37], v[170:173], v[186:189], v[34:37]
	v_mfma_f32_16x16x32_bf16 v[30:33], v[178:181], v[186:189], v[30:33]
	v_mfma_f32_16x16x32_bf16 v[26:29], v[170:173], v[194:197], v[26:29]
	v_mfma_f32_16x16x32_bf16 v[22:25], v[178:181], v[194:197], v[22:25]
	v_mfma_f32_16x16x32_bf16 v[18:21], v[170:173], v[224:227], v[18:21]
	v_mfma_f32_16x16x32_bf16 v[14:17], v[178:181], v[224:227], v[14:17]
	v_mfma_f32_16x16x32_bf16 v[10:13], v[170:173], v[232:235], v[8:11]
	v_mfma_f32_16x16x32_bf16 v[6:9], v[178:181], v[232:235], v[4:7]
	s_setprio 0
	s_barrier
	s_cmp_ge_i32 s69, s54
	s_mov_b32 s46, s69
	s_cbranch_scc0 .LBB0_2023
	s_add_i32 s48, s35, 0x1c000
	s_mov_b32 s70, 0x18000
	s_mov_b32 s71, 0x1c000
	s_add_i32 s72, s35, 0x14000
	s_mov_b32 s72, 0x8000

; #define PG8_STAGE(bufoff, gbase, voff) do { _Pragma("unroll") for (int _i = 0; _i < 2; ++_i) \
;         __builtin_amdgcn_global_load_lds((const unsigned*)((const char*)(gbase) + (voff)[_i]), (LAS unsigned*)(lds + (bufoff) + ldsw + _i * 8192), 16, 0, 0); } while (0)
; #define PG8_LDA(dst, b, h) do { _Pragma("unroll") for (int m = 0; m < 4; ++m) _Pragma("unroll") for (int k = 0; k < 2; ++k) dst[m][k] = *(const LAS bf16x8*)(lds + PG8_SA(b, h) + aoff + m * 2048 + k * 1024); } while (0)
; #define PG8_LDB(dst, b, h) do { _Pragma("unroll") for (int n = 0; n < 2; ++n) _Pragma("unroll") for (int k = 0; k < 2; ++k) dst[n][k] = *(const LAS bf16x8*)(lds + PG8_SB(b, h) + boff + n * 2048 + k * 1024); } while (0)
; #define PG8_MMA(ai, bj, At, Bt) do { __builtin_amdgcn_s_setprio(1); _Pragma("unroll") for (int m = 0; m < 4; ++m) _Pragma("unroll") for (int n = 0; n < 2; ++n) _Pragma("unroll") for (int k = 0; k < 2; ++k) \
;         acc[ai][bj][m][n] = __builtin_amdgcn_mfma_f32_16x16x32_bf16(Bt[n][k], At[m][k], acc[ai][bj][m][n], 0, 0, 0); __builtin_amdgcn_s_setprio(0); } while (0)
; #define PG8_WAIT_V(n) asm volatile("s_waitcnt vmcnt(" #n ")" ::: "memory")
; #define PG8_WAIT_L(n) asm volatile("s_waitcnt lgkmcnt(" #n ")" ::: "memory")
; #define PG8_BAR __builtin_amdgcn_s_barrier()
; #define PG8_WAIT_RELAX(flag, n) asm volatile("s_cmp_eq_u32 %0, 0\n\ts_cbranch_scc1 .Lrw%=\n\ts_waitcnt vmcnt(8)\n.Lrw%=:\n\ts_waitcnt vmcnt(%1)" :: "s"(flag), "n"(n) : "scc", "memory")
; #define PG8_SCHED __builtin_amdgcn_sched_barrier(0)
; template <class Epi, bool ALIGN_EPI = true>
; __device__ __forceinline__ void gemm_phase(LAS unsigned char* lds, const Gemm g, const Sched& S, const Epi& E) {
;     ...
;             PG8_LDB(B0, 0, 0); PG8_LDB(B1, 0, 1); PG8_SCHED; PG8_LDA(At, 0, 0); PG8_STAGE(PG8_SA(1, 1), a1 + hstepA, voffA);
;             if constexpr (Epi::NSTORES > 0) PG8_WAIT_RELAX(rflag, 8 + Epi::NSTORES); else PG8_WAIT_V(8);
;             PG8_WAIT_L(0); PG8_BAR; PG8_MMA(0, 0, At, B0); PG8_MMA(0, 1, At, B1); PG8_BAR; PG8_SCHED;
;             PG8_LDA(At, 0, 1); PG8_STAGE(PG8_SB(0, 0), b2, voffB); PG8_STAGE(PG8_SB(0, 1), b2 + hstepB, voffB); PG8_STAGE(PG8_SA(0, 0), a2, voffA);
;             if constexpr (Epi::NSTORES > 0) PG8_WAIT_RELAX(rflag, 8 + Epi::NSTORES); else PG8_WAIT_V(8);
;             PG8_WAIT_L(0); PG8_BAR; PG8_MMA(1, 0, At, B0); PG8_MMA(1, 1, At, B1); PG8_BAR; PG8_SCHED;
.LBB0_2287:
	s_add_i32 s69, s44, 2
	s_add_u32 s42, s48, 0x100
	s_addc_u32 s43, s49, 0
	s_cmp_eq_u32 s57, s44
	s_cselect_b32 s47, s63, s43
	s_cselect_b32 s46, s64, s42
	s_cselect_b32 s45, s65, s68
	s_cselect_b32 s44, s66, s67
	s_add_u32 s100, s48, 0xffea0000
	s_addc_u32 s101, s49, -1
	ds_read_b128 v[150:153], v147
	ds_read_b128 v[154:157], v147 offset:1024
	ds_read_b128 v[158:161], v147 offset:2048
	ds_read_b128 v[162:165], v147 offset:3072
	ds_read_b128 v[166:169], v147 offset:16384
	ds_read_b128 v[170:173], v147 offset:17408
	ds_read_b128 v[174:177], v147 offset:18432
	ds_read_b128 v[178:181], v147 offset:19456
	ds_read_b128 v[182:185], v148
	ds_read_b128 v[186:189], v148 offset:1024
	ds_read_b128 v[190:193], v148 offset:2048
	ds_read_b128 v[194:197], v148 offset:3072
	s_mov_b32 m0, s55
	ds_read_b128 v[206:209], v148 offset:4096
	global_load_lds_dwordx4 v142, s[100:101]
	s_mov_b32 m0, s56
	ds_read_b128 v[224:227], v148 offset:5120
	global_load_lds_dwordx4 v144, s[100:101]
	s_add_i32 m0, s50, 0xc000
	ds_read_b128 v[228:231], v148 offset:6144
	global_load_lds_dwordx4 v142, s[48:49]
	s_add_i32 m0, s50, 0xe000
	ds_read_b128 v[232:235], v148 offset:7168
	global_load_lds_dwordx4 v144, s[48:49]
	s_waitcnt vmcnt(8) lgkmcnt(0)
	s_barrier
	s_setprio 1
	v_mfma_f32_16x16x32_bf16 v[130:133], v[150:153], v[182:185], v[130:133]
	v_mfma_f32_16x16x32_bf16 v[126:129], v[158:161], v[182:185], v[126:129]
	v_mfma_f32_16x16x32_bf16 v[114:117], v[150:153], v[190:193], v[114:117]
	v_mfma_f32_16x16x32_bf16 v[110:113], v[158:161], v[190:193], v[110:113]
	v_mfma_f32_16x16x32_bf16 v[98:101], v[150:153], v[206:209], v[98:101]
	v_mfma_f32_16x16x32_bf16 v[94:97], v[158:161], v[206:209], v[94:97]
	v_mfma_f32_16x16x32_bf16 v[82:85], v[150:153], v[228:231], v[82:85]
	v_mfma_f32_16x16x32_bf16 v[78:81], v[158:161], v[228:231], v[78:81]
	v_mfma_f32_16x16x32_bf16 v[130:133], v[154:157], v[186:189], v[130:133]
	v_mfma_f32_16x16x32_bf16 v[126:129], v[162:165], v[186:189], v[126:129]
	v_mfma_f32_16x16x32_bf16 v[114:117], v[154:157], v[194:197], v[114:117]
	v_mfma_f32_16x16x32_bf16 v[110:113], v[162:165], v[194:197], v[110:113]
	v_mfma_f32_16x16x32_bf16 v[98:101], v[154:157], v[224:227], v[98:101]
	v_mfma_f32_16x16x32_bf16 v[94:97], v[162:165], v[224:227], v[94:97]
	v_mfma_f32_16x16x32_bf16 v[82:85], v[154:157], v[232:235], v[82:85]
	v_mfma_f32_16x16x32_bf16 v[78:81], v[162:165], v[232:235], v[78:81]
	s_setprio 0
	s_setprio 1
	v_mfma_f32_16x16x32_bf16 v[122:125], v[166:169], v[182:185], v[122:125]
	v_mfma_f32_16x16x32_bf16 v[118:121], v[174:177], v[182:185], v[118:121]
	v_mfma_f32_16x16x32_bf16 v[106:109], v[166:169], v[190:193], v[106:109]
	v_mfma_f32_16x16x32_bf16 v[102:105], v[174:177], v[190:193], v[102:105]
	v_mfma_f32_16x16x32_bf16 v[90:93], v[166:169], v[206:209], v[90:93]
	v_mfma_f32_16x16x32_bf16 v[86:89], v[174:177], v[206:209], v[86:89]
	v_mfma_f32_16x16x32_bf16 v[74:77], v[166:169], v[228:231], v[74:77]
	v_mfma_f32_16x16x32_bf16 v[70:73], v[174:177], v[228:231], v[70:73]
	v_mfma_f32_16x16x32_bf16 v[122:125], v[170:173], v[186:189], v[122:125]
	v_mfma_f32_16x16x32_bf16 v[118:121], v[178:181], v[186:189], v[118:121]
	v_mfma_f32_16x16x32_bf16 v[106:109], v[170:173], v[194:197], v[106:109]
	v_mfma_f32_16x16x32_bf16 v[102:105], v[178:181], v[194:197], v[102:105]
	v_mfma_f32_16x16x32_bf16 v[90:93], v[170:173], v[224:227], v[90:93]
	v_mfma_f32_16x16x32_bf16 v[86:89], v[178:181], v[224:227], v[86:89]
	v_mfma_f32_16x16x32_bf16 v[74:77], v[170:173], v[232:235], v[74:77]
	v_mfma_f32_16x16x32_bf16 v[70:73], v[178:181], v[232:235], v[70:73]
	s_setprio 0
	s_barrier
	s_add_u32 s48, s44, 0x160000
	s_addc_u32 s49, s45, 0
	ds_read_b128 v[182:185], v148 offset:16384
	ds_read_b128 v[186:189], v148 offset:17408
	ds_read_b128 v[190:193], v148 offset:18432
	ds_read_b128 v[194:197], v148 offset:19456
	s_add_i32 m0, s37, 0x10000
	ds_read_b128 v[206:209], v148 offset:20480
	global_load_lds_dwordx4 v138, s[44:45]
	s_add_i32 m0, s37, 0x12000
	ds_read_b128 v[224:227], v148 offset:21504
	global_load_lds_dwordx4 v134, s[44:45]
	s_add_i32 m0, s37, 0x14000
	ds_read_b128 v[228:231], v148 offset:22528
	global_load_lds_dwordx4 v138, s[48:49]
	s_add_i32 m0, s37, 0x16000
	ds_read_b128 v[232:235], v148 offset:23552
	global_load_lds_dwordx4 v134, s[48:49]
	s_waitcnt vmcnt(6) lgkmcnt(0)
	s_barrier
	s_setprio 1
	v_mfma_f32_16x16x32_bf16 v[66:69], v[150:153], v[182:185], v[66:69]
	v_mfma_f32_16x16x32_bf16 v[62:65], v[158:161], v[182:185], v[62:65]
	v_mfma_f32_16x16x32_bf16 v[50:53], v[150:153], v[190:193], v[50:53]
	v_mfma_f32_16x16x32_bf16 v[46:49], v[158:161], v[190:193], v[46:49]
	v_mfma_f32_16x16x32_bf16 v[34:37], v[150:153], v[206:209], v[34:37]
	v_mfma_f32_16x16x32_bf16 v[30:33], v[158:161], v[206:209], v[30:33]
	v_mfma_f32_16x16x32_bf16 v[18:21], v[150:153], v[228:231], v[18:21]
	v_mfma_f32_16x16x32_bf16 v[14:17], v[158:161], v[228:231], v[14:17]
	v_mfma_f32_16x16x32_bf16 v[66:69], v[154:157], v[186:189], v[66:69]
	v_mfma_f32_16x16x32_bf16 v[62:65], v[162:165], v[186:189], v[62:65]
	v_mfma_f32_16x16x32_bf16 v[50:53], v[154:157], v[194:197], v[50:53]
	v_mfma_f32_16x16x32_bf16 v[46:49], v[162:165], v[194:197], v[46:49]
	v_mfma_f32_16x16x32_bf16 v[34:37], v[154:157], v[224:227], v[34:37]
	v_mfma_f32_16x16x32_bf16 v[30:33], v[162:165], v[224:227], v[30:33]
	v_mfma_f32_16x16x32_bf16 v[18:21], v[154:157], v[232:235], v[18:21]
	v_mfma_f32_16x16x32_bf16 v[14:17], v[162:165], v[232:235], v[14:17]
	s_setprio 0
	s_setprio 1
	v_mfma_f32_16x16x32_bf16 v[58:61], v[166:169], v[182:185], v[58:61]
	v_mfma_f32_16x16x32_bf16 v[54:57], v[174:177], v[182:185], v[54:57]
	v_mfma_f32_16x16x32_bf16 v[42:45], v[166:169], v[190:193], v[42:45]
	v_mfma_f32_16x16x32_bf16 v[38:41], v[174:177], v[190:193], v[38:41]
	v_mfma_f32_16x16x32_bf16 v[26:29], v[166:169], v[206:209], v[26:29]
	v_mfma_f32_16x16x32_bf16 v[22:25], v[174:177], v[206:209], v[22:25]
	v_mfma_f32_16x16x32_bf16 v[10:13], v[166:169], v[228:231], v[10:13]
	v_mfma_f32_16x16x32_bf16 v[4:7], v[174:177], v[228:231], v[6:9]
	v_mfma_f32_16x16x32_bf16 v[58:61], v[170:173], v[186:189], v[58:61]
	v_mfma_f32_16x16x32_bf16 v[54:57], v[178:181], v[186:189], v[54:57]
	v_mfma_f32_16x16x32_bf16 v[42:45], v[170:173], v[194:197], v[42:45]
	v_mfma_f32_16x16x32_bf16 v[38:41], v[178:181], v[194:197], v[38:41]
	v_mfma_f32_16x16x32_bf16 v[26:29], v[170:173], v[224:227], v[26:29]
	v_mfma_f32_16x16x32_bf16 v[22:25], v[178:181], v[224:227], v[22:25]
	v_mfma_f32_16x16x32_bf16 v[10:13], v[170:173], v[232:235], v[10:13]
	v_mfma_f32_16x16x32_bf16 v[4:7], v[178:181], v[232:235], v[4:7]
	s_setprio 0
	s_barrier
; #define PG8_STAGE(bufoff, gbase, voff) do { _Pragma("unroll") for (int _i = 0; _i < 2; ++_i) \
;         __builtin_amdgcn_global_load_lds((const unsigned*)((const char*)(gbase) + (voff)[_i]), (LAS unsigned*)(lds + (bufoff) + ldsw + _i * 8192), 16, 0, 0); } while (0)
; #define PG8_LDA(dst, b, h) do { _Pragma("unroll") for (int m = 0; m < 4; ++m) _Pragma("unroll") for (int k = 0; k < 2; ++k) dst[m][k] = *(const LAS bf16x8*)(lds + PG8_SA(b, h) + aoff + m * 2048 + k * 1024); } while (0)
; #define PG8_LDB(dst, b, h) do { _Pragma("unroll") for (int n = 0; n < 2; ++n) _Pragma("unroll") for (int k = 0; k < 2; ++k) dst[n][k] = *(const LAS bf16x8*)(lds + PG8_SB(b, h) + boff + n * 2048 + k * 1024); } while (0)
; #define PG8_MMA(ai, bj, At, Bt) do { __builtin_amdgcn_s_setprio(1); _Pragma("unroll") for (int m = 0; m < 4; ++m) _Pragma("unroll") for (int n = 0; n < 2; ++n) _Pragma("unroll") for (int k = 0; k < 2; ++k) \
;         acc[ai][bj][m][n] = __builtin_amdgcn_mfma_f32_16x16x32_bf16(Bt[n][k], At[m][k], acc[ai][bj][m][n], 0, 0, 0); __builtin_amdgcn_s_setprio(0); } while (0)
; #define PG8_WAIT_V(n) asm volatile("s_waitcnt vmcnt(" #n ")" ::: "memory")
; #define PG8_WAIT_L(n) asm volatile("s_waitcnt lgkmcnt(" #n ")" ::: "memory")
; #define PG8_BAR __builtin_amdgcn_s_barrier()
; #define PG8_SCHED __builtin_amdgcn_sched_barrier(0)
; template <class Epi, bool ALIGN_EPI = true>
; __device__ __forceinline__ void gemm_phase(LAS unsigned char* lds, const Gemm g, const Sched& S, const Epi& E) {
;     ...
;             PG8_LDB(B0, 1, 0); PG8_LDB(B1, 1, 1); PG8_SCHED; PG8_LDA(At, 1, 0); PG8_STAGE(PG8_SA(0, 1), a2 + hstepA, voffA);
;             PG8_WAIT_V(8); PG8_WAIT_L(0); PG8_BAR; PG8_MMA(0, 0, At, B0); PG8_MMA(0, 1, At, B1); PG8_BAR; PG8_SCHED;
;             PG8_LDA(At, 1, 1); PG8_STAGE(PG8_SB(1, 0), b3, voffB); PG8_STAGE(PG8_SB(1, 1), b3 + hstepB, voffB); PG8_STAGE(PG8_SA(1, 0), a3, voffA);
;             PG8_WAIT_V(8); PG8_WAIT_L(0); PG8_BAR; PG8_MMA(1, 0, At, B0); PG8_MMA(1, 1, At, B1); PG8_BAR; PG8_SCHED;
	s_mov_b64 s[100:101], s[46:47]
	s_add_u32 s46, s46, 0x160000
	s_addc_u32 s47, s47, 0
	ds_read_b128 v[150:153], v147 offset:32768
	ds_read_b128 v[154:157], v147 offset:33792
	ds_read_b128 v[158:161], v147 offset:34816
	ds_read_b128 v[162:165], v147 offset:35840
	ds_read_b128 v[166:169], v147 offset:49152
	ds_read_b128 v[170:173], v147 offset:50176
	ds_read_b128 v[174:177], v147 offset:51200
	ds_read_b128 v[178:181], v147 offset:52224
	ds_read_b128 v[182:185], v148 offset:32768
	ds_read_b128 v[186:189], v148 offset:33792
	ds_read_b128 v[190:193], v148 offset:34816
	ds_read_b128 v[194:197], v148 offset:35840
	s_mov_b32 m0, s50
	ds_read_b128 v[206:209], v148 offset:36864
	global_load_lds_dwordx4 v140, s[100:101]
	s_mov_b32 m0, s51
	ds_read_b128 v[224:227], v148 offset:37888
	global_load_lds_dwordx4 v136, s[100:101]
	s_mov_b32 m0, s52
	ds_read_b128 v[228:231], v148 offset:38912
	global_load_lds_dwordx4 v140, s[46:47]
	s_mov_b32 m0, s53
	ds_read_b128 v[232:235], v148 offset:39936
	global_load_lds_dwordx4 v136, s[46:47]
	s_waitcnt vmcnt(8) lgkmcnt(0)
	s_barrier
	s_setprio 1
	v_mfma_f32_16x16x32_bf16 v[130:133], v[150:153], v[182:185], v[130:133]
	v_mfma_f32_16x16x32_bf16 v[126:129], v[158:161], v[182:185], v[126:129]
	v_mfma_f32_16x16x32_bf16 v[114:117], v[150:153], v[190:193], v[114:117]
	v_mfma_f32_16x16x32_bf16 v[110:113], v[158:161], v[190:193], v[110:113]
	v_mfma_f32_16x16x32_bf16 v[98:101], v[150:153], v[206:209], v[98:101]
	v_mfma_f32_16x16x32_bf16 v[94:97], v[158:161], v[206:209], v[94:97]
	v_mfma_f32_16x16x32_bf16 v[82:85], v[150:153], v[228:231], v[82:85]
	v_mfma_f32_16x16x32_bf16 v[78:81], v[158:161], v[228:231], v[78:81]
	v_mfma_f32_16x16x32_bf16 v[130:133], v[154:157], v[186:189], v[130:133]
	v_mfma_f32_16x16x32_bf16 v[126:129], v[162:165], v[186:189], v[126:129]
	v_mfma_f32_16x16x32_bf16 v[114:117], v[154:157], v[194:197], v[114:117]
	v_mfma_f32_16x16x32_bf16 v[110:113], v[162:165], v[194:197], v[110:113]
	v_mfma_f32_16x16x32_bf16 v[98:101], v[154:157], v[224:227], v[98:101]
	v_mfma_f32_16x16x32_bf16 v[94:97], v[162:165], v[224:227], v[94:97]
	v_mfma_f32_16x16x32_bf16 v[82:85], v[154:157], v[232:235], v[82:85]
	v_mfma_f32_16x16x32_bf16 v[78:81], v[162:165], v[232:235], v[78:81]
	s_setprio 0
	s_setprio 1
	v_mfma_f32_16x16x32_bf16 v[122:125], v[166:169], v[182:185], v[122:125]
	v_mfma_f32_16x16x32_bf16 v[118:121], v[174:177], v[182:185], v[118:121]
	v_mfma_f32_16x16x32_bf16 v[106:109], v[166:169], v[190:193], v[106:109]
	v_mfma_f32_16x16x32_bf16 v[102:105], v[174:177], v[190:193], v[102:105]
	v_mfma_f32_16x16x32_bf16 v[90:93], v[166:169], v[206:209], v[90:93]
	v_mfma_f32_16x16x32_bf16 v[86:89], v[174:177], v[206:209], v[86:89]
	v_mfma_f32_16x16x32_bf16 v[74:77], v[166:169], v[228:231], v[74:77]
	v_mfma_f32_16x16x32_bf16 v[70:73], v[174:177], v[228:231], v[70:73]
	v_mfma_f32_16x16x32_bf16 v[122:125], v[170:173], v[186:189], v[122:125]
	v_mfma_f32_16x16x32_bf16 v[118:121], v[178:181], v[186:189], v[118:121]
	v_mfma_f32_16x16x32_bf16 v[106:109], v[170:173], v[194:197], v[106:109]
	v_mfma_f32_16x16x32_bf16 v[102:105], v[178:181], v[194:197], v[102:105]
	v_mfma_f32_16x16x32_bf16 v[90:93], v[170:173], v[224:227], v[90:93]
	v_mfma_f32_16x16x32_bf16 v[86:89], v[178:181], v[224:227], v[86:89]
	v_mfma_f32_16x16x32_bf16 v[74:77], v[170:173], v[232:235], v[74:77]
	v_mfma_f32_16x16x32_bf16 v[70:73], v[178:181], v[232:235], v[70:73]
	s_setprio 0
	s_barrier
	ds_read_b128 v[182:185], v148 offset:49152
	ds_read_b128 v[186:189], v148 offset:50176
	ds_read_b128 v[190:193], v148 offset:51200
	ds_read_b128 v[194:197], v148 offset:52224
	s_add_i32 m0, s37, 0x17f80
	ds_read_b128 v[206:209], v148 offset:53248
	global_load_lds_dwordx4 v138, s[44:45] offset:128
	s_add_i32 m0, s37, 0x19f80
	ds_read_b128 v[224:227], v148 offset:54272
	global_load_lds_dwordx4 v134, s[44:45] offset:128
	s_add_i32 m0, s37, 0x1c000
	s_add_u32 s44, s44, 0x160080
	s_addc_u32 s45, s45, 0
	ds_read_b128 v[228:231], v148 offset:55296
	global_load_lds_dwordx4 v138, s[44:45]
	s_add_i32 m0, s37, 0x1e000
	ds_read_b128 v[232:235], v148 offset:56320
	global_load_lds_dwordx4 v134, s[44:45]
	s_waitcnt vmcnt(6) lgkmcnt(0)
	s_barrier
	s_setprio 1
	v_mfma_f32_16x16x32_bf16 v[66:69], v[150:153], v[182:185], v[66:69]
	v_mfma_f32_16x16x32_bf16 v[62:65], v[158:161], v[182:185], v[62:65]
	v_mfma_f32_16x16x32_bf16 v[50:53], v[150:153], v[190:193], v[50:53]
	v_mfma_f32_16x16x32_bf16 v[46:49], v[158:161], v[190:193], v[46:49]
	v_mfma_f32_16x16x32_bf16 v[34:37], v[150:153], v[206:209], v[34:37]
	v_mfma_f32_16x16x32_bf16 v[30:33], v[158:161], v[206:209], v[30:33]
	v_mfma_f32_16x16x32_bf16 v[18:21], v[150:153], v[228:231], v[18:21]
	v_mfma_f32_16x16x32_bf16 v[14:17], v[158:161], v[228:231], v[14:17]
	v_mfma_f32_16x16x32_bf16 v[66:69], v[154:157], v[186:189], v[66:69]
	v_mfma_f32_16x16x32_bf16 v[62:65], v[162:165], v[186:189], v[62:65]
	v_mfma_f32_16x16x32_bf16 v[50:53], v[154:157], v[194:197], v[50:53]
	v_mfma_f32_16x16x32_bf16 v[46:49], v[162:165], v[194:197], v[46:49]
	v_mfma_f32_16x16x32_bf16 v[34:37], v[154:157], v[224:227], v[34:37]
	v_mfma_f32_16x16x32_bf16 v[30:33], v[162:165], v[224:227], v[30:33]
	v_mfma_f32_16x16x32_bf16 v[18:21], v[154:157], v[232:235], v[18:21]
	v_mfma_f32_16x16x32_bf16 v[14:17], v[162:165], v[232:235], v[14:17]
	s_setprio 0
	s_setprio 1
	s_add_u32 s67, s67, 0x100
	s_addc_u32 s68, s68, 0
	v_mfma_f32_16x16x32_bf16 v[58:61], v[166:169], v[182:185], v[58:61]
	v_mfma_f32_16x16x32_bf16 v[54:57], v[174:177], v[182:185], v[54:57]
	v_mfma_f32_16x16x32_bf16 v[42:45], v[166:169], v[190:193], v[42:45]
	v_mfma_f32_16x16x32_bf16 v[38:41], v[174:177], v[190:193], v[38:41]
	v_mfma_f32_16x16x32_bf16 v[26:29], v[166:169], v[206:209], v[26:29]
	v_mfma_f32_16x16x32_bf16 v[22:25], v[174:177], v[206:209], v[22:25]
	v_mfma_f32_16x16x32_bf16 v[8:11], v[166:169], v[228:231], v[10:13]
	v_mfma_f32_16x16x32_bf16 v[4:7], v[174:177], v[228:231], v[4:7]
	v_mfma_f32_16x16x32_bf16 v[58:61], v[170:173], v[186:189], v[58:61]
	v_mfma_f32_16x16x32_bf16 v[54:57], v[178:181], v[186:189], v[54:57]
	v_mfma_f32_16x16x32_bf16 v[42:45], v[170:173], v[194:197], v[42:45]
	v_mfma_f32_16x16x32_bf16 v[38:41], v[178:181], v[194:197], v[38:41]
	v_mfma_f32_16x16x32_bf16 v[26:29], v[170:173], v[224:227], v[26:29]
	v_mfma_f32_16x16x32_bf16 v[22:25], v[178:181], v[224:227], v[22:25]
	v_mfma_f32_16x16x32_bf16 v[10:13], v[170:173], v[232:235], v[8:11]
	v_mfma_f32_16x16x32_bf16 v[6:9], v[178:181], v[232:235], v[4:7]
	s_setprio 0
	s_barrier
	s_cmp_ge_i32 s69, s54
	s_mov_b64 s[48:49], s[42:43]
	s_mov_b32 s44, s69
	s_cbranch_scc0 .LBB0_2287
	s_add_i32 s46, s37, 0x1c000
	s_add_i32 s70, s37, 0x14000
	s_mov_b32 s71, 0x14000
